# GEMM epilogue stores with sc1 (write-through) so the grid barrier's L2 writeback has less to flush
# speedup vs baseline: 1.0002x; 1.0002x over previous
; __device__ __forceinline__ unsigned cvt_pk_bf16(float lo, float hi) { unsigned r; asm volatile("v_cvt_pk_bf16_f32 %0, %1, %2" : "=v"(r) : "v"(lo), "v"(hi)); return r; }
;     static __device__ __forceinline__ float sw(float g, float up) { return g * __builtin_amdgcn_rcpf(1.0f + __builtin_amdgcn_exp2f(-1.4426950408889634f * g)) * up; }
;     __device__ __forceinline__ void operator()(const f32x4 (&acc)[2][2][4][2], const Unit& u, int wr, int wc, int fr, int fq) const {
;         const int row0 = u.pm * BM + wr * 64 + fr, col0 = u.pn * HALF + wc * 32 + 8 * fq;
; #pragma unroll
;         for (int ai = 0; ai < 2; ++ai)
; #pragma unroll
;             for (int m = 0; m < 4; ++m) { bf16_t* rowp = Hout + (size_t)(row0 + ai * HALF + m * 16) * ldc + col0;
;                 const f32x4 g0 = acc[ai][0][m][0], g1 = acc[ai][0][m][1], u0 = acc[ai][1][m][0], u1 = acc[ai][1][m][1];
;                 u32x4 w; w.x = cvt_pk_bf16(sw(g0[0], u0[0]), sw(g0[1], u0[1])); w.y = cvt_pk_bf16(sw(g0[2], u0[2]), sw(g0[3], u0[3]));
;                 w.z = cvt_pk_bf16(sw(g1[0], u1[0]), sw(g1[1], u1[1])); w.w = cvt_pk_bf16(sw(g1[2], u1[2]), sw(g1[3], u1[3]));
;                 *(u32x4*)rowp = w; }
.LBB0_327:
	s_cmp_lg_u32 s57, 1
	v_mul_lo_u32 v132, s45, v170
	s_cbranch_scc0 .LBB0_329
	v_lshl_or_b32 v130, s73, 7, v200
	v_ashrrev_i32_e32 v133, 31, v170
	v_ashrrev_i32_e32 v131, 31, v130
	v_mul_lo_u32 v133, s44, v133
	v_mad_u64_u32 v[134:135], s[12:13], s44, v170, 0
	v_lshl_add_u64 v[130:131], v[130:131], 1, s[8:9]
	v_add3_u32 v135, v135, v133, v132
	v_lshl_add_u64 v[138:139], v[134:135], 1, v[130:131]
	s_mov_b32 s14, 0xbfb8aa3b
	s_mov_b32 s15, 0
	s_mov_b32 s42, 1.0
	s_mov_b32 s43, 0
	s_mov_b32 s16, 0x2c000
	s_mov_b32 s17, 0
	v_pk_mul_f32 v[202:203], v[126:127], s[14:15] op_sel_hi:[1,0]
	v_pk_mul_f32 v[204:205], v[128:129], s[14:15] op_sel_hi:[1,0]
	v_pk_mul_f32 v[206:207], v[122:123], s[14:15] op_sel_hi:[1,0]
	v_pk_mul_f32 v[208:209], v[124:125], s[14:15] op_sel_hi:[1,0]
	v_exp_f32_e32 v202, v202
	v_exp_f32_e32 v203, v203
	v_exp_f32_e32 v204, v204
	v_exp_f32_e32 v205, v205
	v_exp_f32_e32 v206, v206
	v_exp_f32_e32 v207, v207
	v_exp_f32_e32 v208, v208
	v_exp_f32_e32 v209, v209
	v_pk_add_f32 v[202:203], v[202:203], s[42:43] op_sel_hi:[1,0]
	v_pk_add_f32 v[204:205], v[204:205], s[42:43] op_sel_hi:[1,0]
	v_pk_add_f32 v[206:207], v[206:207], s[42:43] op_sel_hi:[1,0]
	v_pk_add_f32 v[208:209], v[208:209], s[42:43] op_sel_hi:[1,0]
	v_rcp_f32_e32 v202, v202
	v_rcp_f32_e32 v203, v203
	v_rcp_f32_e32 v204, v204
	v_rcp_f32_e32 v205, v205
	v_rcp_f32_e32 v206, v206
	v_rcp_f32_e32 v207, v207
	v_rcp_f32_e32 v208, v208
	v_rcp_f32_e32 v209, v209
	v_pk_mul_f32 v[202:203], v[126:127], v[202:203]
	v_pk_mul_f32 v[204:205], v[128:129], v[204:205]
	v_pk_mul_f32 v[206:207], v[122:123], v[206:207]
	v_pk_mul_f32 v[208:209], v[124:125], v[208:209]
	v_pk_mul_f32 v[202:203], v[202:203], v[118:119]
	v_pk_mul_f32 v[204:205], v[204:205], v[120:121]
	v_pk_mul_f32 v[206:207], v[206:207], v[114:115]
	v_pk_mul_f32 v[208:209], v[208:209], v[116:117]
	v_cvt_pk_bf16_f32 v210, v202, v203
	v_cvt_pk_bf16_f32 v211, v204, v205
	v_cvt_pk_bf16_f32 v212, v206, v207
	v_cvt_pk_bf16_f32 v213, v208, v209
	s_nop 0
	global_store_dwordx4 v[138:139], v[210:213], off sc1
	s_nop 1
	v_lshl_add_u64 v[138:139], v[138:139], 0, s[16:17]
	v_pk_mul_f32 v[216:217], v[110:111], s[14:15] op_sel_hi:[1,0]
	v_pk_mul_f32 v[218:219], v[112:113], s[14:15] op_sel_hi:[1,0]
	v_pk_mul_f32 v[220:221], v[106:107], s[14:15] op_sel_hi:[1,0]
	v_pk_mul_f32 v[222:223], v[108:109], s[14:15] op_sel_hi:[1,0]
	v_exp_f32_e32 v216, v216
	v_exp_f32_e32 v217, v217
	v_exp_f32_e32 v218, v218
	v_exp_f32_e32 v219, v219
	v_exp_f32_e32 v220, v220
	v_exp_f32_e32 v221, v221
	v_exp_f32_e32 v222, v222
	v_exp_f32_e32 v223, v223
	v_pk_add_f32 v[216:217], v[216:217], s[42:43] op_sel_hi:[1,0]
	v_pk_add_f32 v[218:219], v[218:219], s[42:43] op_sel_hi:[1,0]
	v_pk_add_f32 v[220:221], v[220:221], s[42:43] op_sel_hi:[1,0]
	v_pk_add_f32 v[222:223], v[222:223], s[42:43] op_sel_hi:[1,0]
	v_rcp_f32_e32 v216, v216
	v_rcp_f32_e32 v217, v217
	v_rcp_f32_e32 v218, v218
	v_rcp_f32_e32 v219, v219
	v_rcp_f32_e32 v220, v220
	v_rcp_f32_e32 v221, v221
	v_rcp_f32_e32 v222, v222
	v_rcp_f32_e32 v223, v223
	v_pk_mul_f32 v[216:217], v[110:111], v[216:217]
	v_pk_mul_f32 v[218:219], v[112:113], v[218:219]
	v_pk_mul_f32 v[220:221], v[106:107], v[220:221]
	v_pk_mul_f32 v[222:223], v[108:109], v[222:223]
	v_pk_mul_f32 v[216:217], v[216:217], v[102:103]
	v_pk_mul_f32 v[218:219], v[218:219], v[104:105]
	v_pk_mul_f32 v[220:221], v[220:221], v[98:99]
	v_pk_mul_f32 v[222:223], v[222:223], v[100:101]
	v_cvt_pk_bf16_f32 v224, v216, v217
	v_cvt_pk_bf16_f32 v225, v218, v219
	v_cvt_pk_bf16_f32 v226, v220, v221
	v_cvt_pk_bf16_f32 v227, v222, v223
	s_nop 0
	global_store_dwordx4 v[138:139], v[224:227], off sc1
	s_nop 1
	v_lshl_add_u64 v[138:139], v[138:139], 0, s[16:17]
	v_pk_mul_f32 v[202:203], v[94:95], s[14:15] op_sel_hi:[1,0]
	v_pk_mul_f32 v[204:205], v[96:97], s[14:15] op_sel_hi:[1,0]
	v_pk_mul_f32 v[206:207], v[90:91], s[14:15] op_sel_hi:[1,0]
	v_pk_mul_f32 v[208:209], v[92:93], s[14:15] op_sel_hi:[1,0]
	v_exp_f32_e32 v202, v202
	v_exp_f32_e32 v203, v203
	v_exp_f32_e32 v204, v204
	v_exp_f32_e32 v205, v205
	v_exp_f32_e32 v206, v206
	v_exp_f32_e32 v207, v207
	v_exp_f32_e32 v208, v208
	v_exp_f32_e32 v209, v209
	v_pk_add_f32 v[202:203], v[202:203], s[42:43] op_sel_hi:[1,0]
	v_pk_add_f32 v[204:205], v[204:205], s[42:43] op_sel_hi:[1,0]
	v_pk_add_f32 v[206:207], v[206:207], s[42:43] op_sel_hi:[1,0]
	v_pk_add_f32 v[208:209], v[208:209], s[42:43] op_sel_hi:[1,0]
	v_rcp_f32_e32 v202, v202
	v_rcp_f32_e32 v203, v203
	v_rcp_f32_e32 v204, v204
	v_rcp_f32_e32 v205, v205
	v_rcp_f32_e32 v206, v206
	v_rcp_f32_e32 v207, v207
	v_rcp_f32_e32 v208, v208
	v_rcp_f32_e32 v209, v209
	v_pk_mul_f32 v[202:203], v[94:95], v[202:203]
	v_pk_mul_f32 v[204:205], v[96:97], v[204:205]
	v_pk_mul_f32 v[206:207], v[90:91], v[206:207]
	v_pk_mul_f32 v[208:209], v[92:93], v[208:209]
	v_pk_mul_f32 v[202:203], v[202:203], v[86:87]
	v_pk_mul_f32 v[204:205], v[204:205], v[88:89]
	v_pk_mul_f32 v[206:207], v[206:207], v[82:83]
	v_pk_mul_f32 v[208:209], v[208:209], v[84:85]
	v_cvt_pk_bf16_f32 v210, v202, v203
	v_cvt_pk_bf16_f32 v211, v204, v205
	v_cvt_pk_bf16_f32 v212, v206, v207
	v_cvt_pk_bf16_f32 v213, v208, v209
	s_nop 0
	global_store_dwordx4 v[138:139], v[210:213], off sc1
	s_nop 1
	v_lshl_add_u64 v[138:139], v[138:139], 0, s[16:17]
	v_pk_mul_f32 v[216:217], v[78:79], s[14:15] op_sel_hi:[1,0]
	v_pk_mul_f32 v[218:219], v[80:81], s[14:15] op_sel_hi:[1,0]
	v_pk_mul_f32 v[220:221], v[74:75], s[14:15] op_sel_hi:[1,0]
	v_pk_mul_f32 v[222:223], v[76:77], s[14:15] op_sel_hi:[1,0]
	v_exp_f32_e32 v216, v216
	v_exp_f32_e32 v217, v217
	v_exp_f32_e32 v218, v218
	v_exp_f32_e32 v219, v219
	v_exp_f32_e32 v220, v220
	v_exp_f32_e32 v221, v221
; __device__ __forceinline__ unsigned cvt_pk_bf16(float lo, float hi) { unsigned r; asm volatile("v_cvt_pk_bf16_f32 %0, %1, %2" : "=v"(r) : "v"(lo), "v"(hi)); return r; }
;     static __device__ __forceinline__ float sw(float g, float up) { return g * __builtin_amdgcn_rcpf(1.0f + __builtin_amdgcn_exp2f(-1.4426950408889634f * g)) * up; }
;     __device__ __forceinline__ void operator()(const f32x4 (&acc)[2][2][4][2], const Unit& u, int wr, int wc, int fr, int fq) const {
;         const int row0 = u.pm * BM + wr * 64 + fr, col0 = u.pn * HALF + wc * 32 + 8 * fq;
; #pragma unroll
;         for (int ai = 0; ai < 2; ++ai)
; #pragma unroll
;             for (int m = 0; m < 4; ++m) { bf16_t* rowp = Hout + (size_t)(row0 + ai * HALF + m * 16) * ldc + col0;
;                 const f32x4 g0 = acc[ai][0][m][0], g1 = acc[ai][0][m][1], u0 = acc[ai][1][m][0], u1 = acc[ai][1][m][1];
;                 u32x4 w; w.x = cvt_pk_bf16(sw(g0[0], u0[0]), sw(g0[1], u0[1])); w.y = cvt_pk_bf16(sw(g0[2], u0[2]), sw(g0[3], u0[3]));
;                 w.z = cvt_pk_bf16(sw(g1[0], u1[0]), sw(g1[1], u1[1])); w.w = cvt_pk_bf16(sw(g1[2], u1[2]), sw(g1[3], u1[3]));
;                 *(u32x4*)rowp = w; }
	v_exp_f32_e32 v222, v222
	v_exp_f32_e32 v223, v223
	v_pk_add_f32 v[216:217], v[216:217], s[42:43] op_sel_hi:[1,0]
	v_pk_add_f32 v[218:219], v[218:219], s[42:43] op_sel_hi:[1,0]
	v_pk_add_f32 v[220:221], v[220:221], s[42:43] op_sel_hi:[1,0]
	v_pk_add_f32 v[222:223], v[222:223], s[42:43] op_sel_hi:[1,0]
	v_rcp_f32_e32 v216, v216
	v_rcp_f32_e32 v217, v217
	v_rcp_f32_e32 v218, v218
	v_rcp_f32_e32 v219, v219
	v_rcp_f32_e32 v220, v220
	v_rcp_f32_e32 v221, v221
	v_rcp_f32_e32 v222, v222
	v_rcp_f32_e32 v223, v223
	v_pk_mul_f32 v[216:217], v[78:79], v[216:217]
	v_pk_mul_f32 v[218:219], v[80:81], v[218:219]
	v_pk_mul_f32 v[220:221], v[74:75], v[220:221]
	v_pk_mul_f32 v[222:223], v[76:77], v[222:223]
	v_pk_mul_f32 v[216:217], v[216:217], v[70:71]
	v_pk_mul_f32 v[218:219], v[218:219], v[72:73]
	v_pk_mul_f32 v[220:221], v[220:221], v[66:67]
	v_pk_mul_f32 v[222:223], v[222:223], v[68:69]
	v_cvt_pk_bf16_f32 v224, v216, v217
	v_cvt_pk_bf16_f32 v225, v218, v219
	v_cvt_pk_bf16_f32 v226, v220, v221
	v_cvt_pk_bf16_f32 v227, v222, v223
	s_nop 0
	global_store_dwordx4 v[138:139], v[224:227], off sc1
	s_nop 1
	s_mov_b32 s16, 0xdc000
	v_lshl_add_u64 v[138:139], v[138:139], 0, s[16:17]
	s_mov_b32 s16, 0x2c000
	v_pk_mul_f32 v[202:203], v[62:63], s[14:15] op_sel_hi:[1,0]
	v_pk_mul_f32 v[204:205], v[64:65], s[14:15] op_sel_hi:[1,0]
	v_pk_mul_f32 v[206:207], v[58:59], s[14:15] op_sel_hi:[1,0]
	v_pk_mul_f32 v[208:209], v[60:61], s[14:15] op_sel_hi:[1,0]
	v_exp_f32_e32 v202, v202
	v_exp_f32_e32 v203, v203
	v_exp_f32_e32 v204, v204
	v_exp_f32_e32 v205, v205
	v_exp_f32_e32 v206, v206
	v_exp_f32_e32 v207, v207
	v_exp_f32_e32 v208, v208
	v_exp_f32_e32 v209, v209
	v_pk_add_f32 v[202:203], v[202:203], s[42:43] op_sel_hi:[1,0]
	v_pk_add_f32 v[204:205], v[204:205], s[42:43] op_sel_hi:[1,0]
	v_pk_add_f32 v[206:207], v[206:207], s[42:43] op_sel_hi:[1,0]
	v_pk_add_f32 v[208:209], v[208:209], s[42:43] op_sel_hi:[1,0]
	v_rcp_f32_e32 v202, v202
	v_rcp_f32_e32 v203, v203
	v_rcp_f32_e32 v204, v204
	v_rcp_f32_e32 v205, v205
	v_rcp_f32_e32 v206, v206
	v_rcp_f32_e32 v207, v207
	v_rcp_f32_e32 v208, v208
	v_rcp_f32_e32 v209, v209
	v_pk_mul_f32 v[202:203], v[62:63], v[202:203]
	v_pk_mul_f32 v[204:205], v[64:65], v[204:205]
	v_pk_mul_f32 v[206:207], v[58:59], v[206:207]
	v_pk_mul_f32 v[208:209], v[60:61], v[208:209]
	v_pk_mul_f32 v[202:203], v[202:203], v[54:55]
	v_pk_mul_f32 v[204:205], v[204:205], v[56:57]
	v_pk_mul_f32 v[206:207], v[206:207], v[50:51]
	v_pk_mul_f32 v[208:209], v[208:209], v[52:53]
	v_cvt_pk_bf16_f32 v210, v202, v203
	v_cvt_pk_bf16_f32 v211, v204, v205
	v_cvt_pk_bf16_f32 v212, v206, v207
	v_cvt_pk_bf16_f32 v213, v208, v209
	s_nop 0
	global_store_dwordx4 v[138:139], v[210:213], off sc1
	s_nop 1
	v_lshl_add_u64 v[138:139], v[138:139], 0, s[16:17]
	v_pk_mul_f32 v[216:217], v[46:47], s[14:15] op_sel_hi:[1,0]
	v_pk_mul_f32 v[218:219], v[48:49], s[14:15] op_sel_hi:[1,0]
	v_pk_mul_f32 v[220:221], v[42:43], s[14:15] op_sel_hi:[1,0]
	v_pk_mul_f32 v[222:223], v[44:45], s[14:15] op_sel_hi:[1,0]
	v_exp_f32_e32 v216, v216
	v_exp_f32_e32 v217, v217
	v_exp_f32_e32 v218, v218
	v_exp_f32_e32 v219, v219
	v_exp_f32_e32 v220, v220
	v_exp_f32_e32 v221, v221
	v_exp_f32_e32 v222, v222
	v_exp_f32_e32 v223, v223
	v_pk_add_f32 v[216:217], v[216:217], s[42:43] op_sel_hi:[1,0]
	v_pk_add_f32 v[218:219], v[218:219], s[42:43] op_sel_hi:[1,0]
	v_pk_add_f32 v[220:221], v[220:221], s[42:43] op_sel_hi:[1,0]
	v_pk_add_f32 v[222:223], v[222:223], s[42:43] op_sel_hi:[1,0]
	v_rcp_f32_e32 v216, v216
	v_rcp_f32_e32 v217, v217
	v_rcp_f32_e32 v218, v218
	v_rcp_f32_e32 v219, v219
	v_rcp_f32_e32 v220, v220
	v_rcp_f32_e32 v221, v221
	v_rcp_f32_e32 v222, v222
	v_rcp_f32_e32 v223, v223
	v_pk_mul_f32 v[216:217], v[46:47], v[216:217]
	v_pk_mul_f32 v[218:219], v[48:49], v[218:219]
	v_pk_mul_f32 v[220:221], v[42:43], v[220:221]
	v_pk_mul_f32 v[222:223], v[44:45], v[222:223]
	v_pk_mul_f32 v[216:217], v[216:217], v[38:39]
	v_pk_mul_f32 v[218:219], v[218:219], v[40:41]
	v_pk_mul_f32 v[220:221], v[220:221], v[34:35]
	v_pk_mul_f32 v[222:223], v[222:223], v[36:37]
	v_cvt_pk_bf16_f32 v224, v216, v217
	v_cvt_pk_bf16_f32 v225, v218, v219
	v_cvt_pk_bf16_f32 v226, v220, v221
	v_cvt_pk_bf16_f32 v227, v222, v223
	s_nop 0
	global_store_dwordx4 v[138:139], v[224:227], off sc1
	s_nop 1
	v_lshl_add_u64 v[138:139], v[138:139], 0, s[16:17]
	v_pk_mul_f32 v[202:203], v[30:31], s[14:15] op_sel_hi:[1,0]
	v_pk_mul_f32 v[204:205], v[32:33], s[14:15] op_sel_hi:[1,0]
	v_pk_mul_f32 v[206:207], v[26:27], s[14:15] op_sel_hi:[1,0]
	v_pk_mul_f32 v[208:209], v[28:29], s[14:15] op_sel_hi:[1,0]
	v_exp_f32_e32 v202, v202
	v_exp_f32_e32 v203, v203
	v_exp_f32_e32 v204, v204
	v_exp_f32_e32 v205, v205
	v_exp_f32_e32 v206, v206
	v_exp_f32_e32 v207, v207
	v_exp_f32_e32 v208, v208
	v_exp_f32_e32 v209, v209
	v_pk_add_f32 v[202:203], v[202:203], s[42:43] op_sel_hi:[1,0]
	v_pk_add_f32 v[204:205], v[204:205], s[42:43] op_sel_hi:[1,0]
	v_pk_add_f32 v[206:207], v[206:207], s[42:43] op_sel_hi:[1,0]
	v_pk_add_f32 v[208:209], v[208:209], s[42:43] op_sel_hi:[1,0]
	v_rcp_f32_e32 v202, v202
	v_rcp_f32_e32 v203, v203
	v_rcp_f32_e32 v204, v204
	v_rcp_f32_e32 v205, v205
	v_rcp_f32_e32 v206, v206
	v_rcp_f32_e32 v207, v207
	v_rcp_f32_e32 v208, v208
	v_rcp_f32_e32 v209, v209
	v_pk_mul_f32 v[202:203], v[30:31], v[202:203]
	v_pk_mul_f32 v[204:205], v[32:33], v[204:205]
	v_pk_mul_f32 v[206:207], v[26:27], v[206:207]
	v_pk_mul_f32 v[208:209], v[28:29], v[208:209]
	v_pk_mul_f32 v[202:203], v[202:203], v[22:23]
	v_pk_mul_f32 v[204:205], v[204:205], v[24:25]
	v_pk_mul_f32 v[206:207], v[206:207], v[18:19]
	v_pk_mul_f32 v[208:209], v[208:209], v[20:21]
	v_cvt_pk_bf16_f32 v210, v202, v203
; __device__ __forceinline__ unsigned cvt_pk_bf16(float lo, float hi) { unsigned r; asm volatile("v_cvt_pk_bf16_f32 %0, %1, %2" : "=v"(r) : "v"(lo), "v"(hi)); return r; }
;     static __device__ __forceinline__ float sw(float g, float up) { return g * __builtin_amdgcn_rcpf(1.0f + __builtin_amdgcn_exp2f(-1.4426950408889634f * g)) * up; }
;     __device__ __forceinline__ void operator()(const f32x4 (&acc)[2][2][4][2], const Unit& u, int wr, int wc, int fr, int fq) const {
;         const int row0 = u.pm * BM + wr * 64 + fr, col0 = u.pn * HALF + wc * 32 + 8 * fq;
; #pragma unroll
;         for (int ai = 0; ai < 2; ++ai)
; #pragma unroll
;             for (int m = 0; m < 4; ++m) { bf16_t* rowp = Hout + (size_t)(row0 + ai * HALF + m * 16) * ldc + col0;
;                 const f32x4 g0 = acc[ai][0][m][0], g1 = acc[ai][0][m][1], u0 = acc[ai][1][m][0], u1 = acc[ai][1][m][1];
;                 u32x4 w; w.x = cvt_pk_bf16(sw(g0[0], u0[0]), sw(g0[1], u0[1])); w.y = cvt_pk_bf16(sw(g0[2], u0[2]), sw(g0[3], u0[3]));
;                 w.z = cvt_pk_bf16(sw(g1[0], u1[0]), sw(g1[1], u1[1])); w.w = cvt_pk_bf16(sw(g1[2], u1[2]), sw(g1[3], u1[3]));
;                 *(u32x4*)rowp = w; }
	v_cvt_pk_bf16_f32 v211, v204, v205
	v_cvt_pk_bf16_f32 v212, v206, v207
	v_cvt_pk_bf16_f32 v213, v208, v209
	s_nop 0
	global_store_dwordx4 v[138:139], v[210:213], off sc1
	s_nop 1
	v_lshl_add_u64 v[138:139], v[138:139], 0, s[16:17]
	v_pk_mul_f32 v[216:217], v[14:15], s[14:15] op_sel_hi:[1,0]
	v_pk_mul_f32 v[218:219], v[16:17], s[14:15] op_sel_hi:[1,0]
	v_pk_mul_f32 v[220:221], v[10:11], s[14:15] op_sel_hi:[1,0]
	v_pk_mul_f32 v[222:223], v[12:13], s[14:15] op_sel_hi:[1,0]
	v_exp_f32_e32 v216, v216
	v_exp_f32_e32 v217, v217
	v_exp_f32_e32 v218, v218
	v_exp_f32_e32 v219, v219
	v_exp_f32_e32 v220, v220
	v_exp_f32_e32 v221, v221
	v_exp_f32_e32 v222, v222
	v_exp_f32_e32 v223, v223
	v_pk_add_f32 v[216:217], v[216:217], s[42:43] op_sel_hi:[1,0]
	v_pk_add_f32 v[218:219], v[218:219], s[42:43] op_sel_hi:[1,0]
	v_pk_add_f32 v[220:221], v[220:221], s[42:43] op_sel_hi:[1,0]
	v_pk_add_f32 v[222:223], v[222:223], s[42:43] op_sel_hi:[1,0]
	v_rcp_f32_e32 v216, v216
	v_rcp_f32_e32 v217, v217
	v_rcp_f32_e32 v218, v218
	v_rcp_f32_e32 v219, v219
	v_rcp_f32_e32 v220, v220
	v_rcp_f32_e32 v221, v221
	v_rcp_f32_e32 v222, v222
	v_rcp_f32_e32 v223, v223
	v_pk_mul_f32 v[216:217], v[14:15], v[216:217]
	v_pk_mul_f32 v[218:219], v[16:17], v[218:219]
	v_pk_mul_f32 v[220:221], v[10:11], v[220:221]
	v_pk_mul_f32 v[222:223], v[12:13], v[222:223]
	v_pk_mul_f32 v[216:217], v[216:217], v[6:7]
	v_pk_mul_f32 v[218:219], v[218:219], v[8:9]
	v_pk_mul_f32 v[220:221], v[220:221], v[2:3]
	v_pk_mul_f32 v[222:223], v[222:223], v[4:5]
	v_cvt_pk_bf16_f32 v224, v216, v217
	v_cvt_pk_bf16_f32 v225, v218, v219
	v_cvt_pk_bf16_f32 v226, v220, v221
	v_cvt_pk_bf16_f32 v227, v222, v223
	s_nop 0
	global_store_dwordx4 v[138:139], v[224:227], off sc1
	s_nop 1
	s_mov_b64 s[12:13], 0
; __device__ __forceinline__ unsigned cvt_pk_bf16(float lo, float hi) { unsigned r; asm volatile("v_cvt_pk_bf16_f32 %0, %1, %2" : "=v"(r) : "v"(lo), "v"(hi)); return r; }
;     __device__ __forceinline__ void plain(const f32x4 (&acc)[2][2][4][2], const Unit& u, int wr, int wc, int fr, int fq) const {
;         const int row0 = u.pm * BM + wr * 64 + fr, col0 = u.pn * BM + wc * 32 + 8 * fq;
; #pragma unroll
;         for (int ai = 0; ai < 2; ++ai)
; #pragma unroll
;             for (int m = 0; m < 4; ++m) { bf16_t* rowp = O + (size_t)(row0 + ai * HALF + m * 16) * ldc + col0;
; #pragma unroll
;                 for (int bj = 0; bj < 2; ++bj) { const f32x4 v0 = acc[ai][bj][m][0], v1 = acc[ai][bj][m][1];
;                     u32x4 w; w.x = cvt_pk_bf16(v0[0], v0[1]); w.y = cvt_pk_bf16(v0[2], v0[3]); w.z = cvt_pk_bf16(v1[0], v1[1]); w.w = cvt_pk_bf16(v1[2], v1[3]);
;                     *(u32x4*)(rowp + bj * HALF) = w; } }
.LBB0_329:
	s_andn2_b64 vcc, exec, s[12:13]
	s_cbranch_vccnz .LBB0_331
	v_lshl_or_b32 v130, s73, 8, v200
	v_ashrrev_i32_e32 v133, 31, v170
	v_ashrrev_i32_e32 v131, 31, v130
	v_mul_lo_u32 v138, s44, v133
	v_mad_u64_u32 v[134:135], s[12:13], s44, v170, 0
	v_lshl_add_u64 v[130:131], v[130:131], 1, s[8:9]
	v_add3_u32 v135, v135, v138, v132
	v_lshl_add_u64 v[136:137], v[134:135], 1, v[130:131]
	v_cvt_pk_bf16_f32 v132, v126, v127
	v_cvt_pk_bf16_f32 v133, v128, v129
	v_cvt_pk_bf16_f32 v134, v122, v123
	v_cvt_pk_bf16_f32 v135, v124, v125
	global_store_dwordx4 v[136:137], v[132:135], off sc1
	s_nop 1
	v_cvt_pk_bf16_f32 v132, v118, v119
	v_cvt_pk_bf16_f32 v133, v120, v121
	v_cvt_pk_bf16_f32 v134, v114, v115
	v_cvt_pk_bf16_f32 v135, v116, v117
	global_store_dwordx4 v[136:137], v[132:135], off offset:256 sc1
	s_nop 1
	v_or_b32_e32 v132, 16, v170
	v_mul_lo_u32 v134, s45, v132
	v_mad_u64_u32 v[132:133], s[12:13], s44, v132, 0
	v_add3_u32 v133, v133, v138, v134
	v_lshl_add_u64 v[136:137], v[132:133], 1, v[130:131]
	v_cvt_pk_bf16_f32 v132, v110, v111
	v_cvt_pk_bf16_f32 v133, v112, v113
	v_cvt_pk_bf16_f32 v134, v106, v107
	v_cvt_pk_bf16_f32 v135, v108, v109
	global_store_dwordx4 v[136:137], v[132:135], off sc1
	s_nop 1
	v_cvt_pk_bf16_f32 v132, v102, v103
	v_cvt_pk_bf16_f32 v133, v104, v105
	v_cvt_pk_bf16_f32 v134, v98, v99
	v_cvt_pk_bf16_f32 v135, v100, v101
	global_store_dwordx4 v[136:137], v[132:135], off offset:256 sc1
	s_nop 1
	v_or_b32_e32 v132, 32, v170
	v_mul_lo_u32 v134, s45, v132
	v_mad_u64_u32 v[132:133], s[12:13], s44, v132, 0
	v_add3_u32 v133, v133, v138, v134
	v_lshl_add_u64 v[136:137], v[132:133], 1, v[130:131]
	v_cvt_pk_bf16_f32 v132, v94, v95
	v_cvt_pk_bf16_f32 v133, v96, v97
	v_cvt_pk_bf16_f32 v134, v90, v91
	v_cvt_pk_bf16_f32 v135, v92, v93
	global_store_dwordx4 v[136:137], v[132:135], off sc1
	s_nop 1
	v_cvt_pk_bf16_f32 v132, v86, v87
	v_cvt_pk_bf16_f32 v133, v88, v89
	v_cvt_pk_bf16_f32 v134, v82, v83
	v_cvt_pk_bf16_f32 v135, v84, v85
	global_store_dwordx4 v[136:137], v[132:135], off offset:256 sc1
	s_nop 1
	v_or_b32_e32 v132, 48, v170
	v_mul_lo_u32 v134, s45, v132
	v_mad_u64_u32 v[132:133], s[12:13], s44, v132, 0
	v_add3_u32 v133, v133, v138, v134
	v_lshl_add_u64 v[136:137], v[132:133], 1, v[130:131]
	v_cvt_pk_bf16_f32 v132, v78, v79
	v_cvt_pk_bf16_f32 v133, v80, v81
	v_cvt_pk_bf16_f32 v134, v74, v75
	v_cvt_pk_bf16_f32 v135, v76, v77
	global_store_dwordx4 v[136:137], v[132:135], off sc1
	s_nop 1
	v_cvt_pk_bf16_f32 v132, v70, v71
	v_cvt_pk_bf16_f32 v133, v72, v73
	v_cvt_pk_bf16_f32 v134, v66, v67
	v_cvt_pk_bf16_f32 v135, v68, v69
	global_store_dwordx4 v[136:137], v[132:135], off offset:256 sc1
	s_nop 1
	v_add_u32_e32 v132, 0x80, v170
	v_ashrrev_i32_e32 v133, 31, v132
	v_mul_lo_u32 v134, s44, v133
	v_mul_lo_u32 v135, s45, v132
	v_mad_u64_u32 v[132:133], s[12:13], s44, v132, 0
	v_add3_u32 v133, v133, v134, v135
	v_lshl_add_u64 v[136:137], v[132:133], 1, v[130:131]
	v_cvt_pk_bf16_f32 v132, v62, v63
	v_cvt_pk_bf16_f32 v133, v64, v65
	v_cvt_pk_bf16_f32 v134, v58, v59
	v_cvt_pk_bf16_f32 v135, v60, v61
	global_store_dwordx4 v[136:137], v[132:135], off sc1
	s_nop 1
	v_cvt_pk_bf16_f32 v132, v54, v55
	v_cvt_pk_bf16_f32 v133, v56, v57
	v_cvt_pk_bf16_f32 v134, v50, v51
	v_cvt_pk_bf16_f32 v135, v52, v53
	global_store_dwordx4 v[136:137], v[132:135], off offset:256 sc1
	s_nop 1
	v_add_u32_e32 v132, 0x90, v170
	v_ashrrev_i32_e32 v133, 31, v132
	v_mul_lo_u32 v134, s44, v133
	v_mul_lo_u32 v135, s45, v132
	v_mad_u64_u32 v[132:133], s[12:13], s44, v132, 0
	v_add3_u32 v133, v133, v134, v135
	v_lshl_add_u64 v[136:137], v[132:133], 1, v[130:131]
	v_cvt_pk_bf16_f32 v132, v46, v47
	v_cvt_pk_bf16_f32 v133, v48, v49
	v_cvt_pk_bf16_f32 v134, v42, v43
	v_cvt_pk_bf16_f32 v135, v44, v45
	global_store_dwordx4 v[136:137], v[132:135], off sc1
	s_nop 1
	v_cvt_pk_bf16_f32 v132, v38, v39
	v_cvt_pk_bf16_f32 v133, v40, v41
	v_cvt_pk_bf16_f32 v134, v34, v35
	v_cvt_pk_bf16_f32 v135, v36, v37
	global_store_dwordx4 v[136:137], v[132:135], off offset:256 sc1
	s_nop 1
	v_add_u32_e32 v132, 0xa0, v170
	v_ashrrev_i32_e32 v133, 31, v132
	v_mul_lo_u32 v134, s44, v133
	v_mul_lo_u32 v135, s45, v132
	v_mad_u64_u32 v[132:133], s[12:13], s44, v132, 0
	v_add3_u32 v133, v133, v134, v135
	v_lshl_add_u64 v[136:137], v[132:133], 1, v[130:131]
	v_cvt_pk_bf16_f32 v132, v30, v31
	v_cvt_pk_bf16_f32 v133, v32, v33
	v_cvt_pk_bf16_f32 v134, v26, v27
	v_cvt_pk_bf16_f32 v135, v28, v29
	global_store_dwordx4 v[136:137], v[132:135], off sc1
	s_nop 1
	v_cvt_pk_bf16_f32 v132, v22, v23
	v_cvt_pk_bf16_f32 v133, v24, v25
	v_cvt_pk_bf16_f32 v134, v18, v19
	v_cvt_pk_bf16_f32 v135, v20, v21
	global_store_dwordx4 v[136:137], v[132:135], off offset:256 sc1
	s_nop 1
	v_add_u32_e32 v132, 0xb0, v170
	v_ashrrev_i32_e32 v133, 31, v132
	v_mul_lo_u32 v134, s44, v133
	v_mul_lo_u32 v135, s45, v132
	v_mad_u64_u32 v[132:133], s[12:13], s44, v132, 0
	v_add3_u32 v133, v133, v134, v135
	v_lshl_add_u64 v[134:135], v[132:133], 1, v[130:131]
	v_cvt_pk_bf16_f32 v130, v14, v15
	v_cvt_pk_bf16_f32 v131, v16, v17
	v_cvt_pk_bf16_f32 v132, v10, v11
	v_cvt_pk_bf16_f32 v133, v12, v13
	global_store_dwordx4 v[134:135], v[130:133], off sc1
	s_nop 1
	v_cvt_pk_bf16_f32 v130, v6, v7
	v_cvt_pk_bf16_f32 v131, v8, v9
	v_cvt_pk_bf16_f32 v132, v2, v3
	v_cvt_pk_bf16_f32 v133, v4, v5
	global_store_dwordx4 v[134:135], v[130:133], off offset:256 sc1

;     __device__ __forceinline__ void operator()(const f32x4 (&acc)[2][2][4][2], const Unit& u, int wr, int wc, int fr, int fq) const {
;     ...
;         } else if (wc == 0) {
; #pragma unroll
;             for (int ai = 0; ai < 2; ++ai)
; #pragma unroll
;                 for (int m = 0; m < 4; ++m) { float* gp = G + (size_t)(row0 + ai * HALF + m * 16) * 32 + 8 * fq;
;                     *(f32x4*)gp = acc[ai][0][m][0]; *(f32x4*)(gp + 4) = acc[ai][0][m][1]; }
.LBB0_332:
	s_cmp_ge_i32 s73, s22
	s_mov_b64 s[12:13], -1
	s_cbranch_scc0 .LBB0_336
	s_andn2_b64 vcc, exec, s[50:51]
	s_cbranch_vccnz .LBB0_335
	v_or_b32_e32 v132, 16, v170
	v_ashrrev_i32_e32 v171, 31, v170
	v_ashrrev_i32_e32 v133, 31, v132
	v_lshlrev_b64 v[130:131], 7, v[170:171]
	v_lshlrev_b64 v[132:133], 7, v[132:133]
	v_lshl_add_u64 v[130:131], v[164:165], 0, v[130:131]
	v_lshl_add_u64 v[132:133], v[164:165], 0, v[132:133]
	global_store_dwordx4 v[130:131], v[126:129], off sc1
	global_store_dwordx4 v[130:131], v[122:125], off offset:16 sc1
	global_store_dwordx4 v[132:133], v[110:113], off sc1
	global_store_dwordx4 v[132:133], v[106:109], off offset:16 sc1
	v_or_b32_e32 v132, 32, v170
	v_ashrrev_i32_e32 v133, 31, v132
	v_lshlrev_b64 v[132:133], 7, v[132:133]
	v_lshl_add_u64 v[132:133], v[164:165], 0, v[132:133]
	global_store_dwordx4 v[132:133], v[94:97], off sc1
	global_store_dwordx4 v[132:133], v[90:93], off offset:16 sc1
	v_or_b32_e32 v132, 48, v170
	v_ashrrev_i32_e32 v133, 31, v132
	v_lshlrev_b64 v[132:133], 7, v[132:133]
	v_lshl_add_u64 v[132:133], v[164:165], 0, v[132:133]
	s_mov_b64 s[12:13], 0x4000
	global_store_dwordx4 v[132:133], v[78:81], off sc1
	global_store_dwordx4 v[132:133], v[74:77], off offset:16 sc1
	v_lshl_add_u64 v[132:133], v[130:131], 0, s[12:13]
	s_movk_i32 s12, 0x4000
	v_add_co_u32_e32 v134, vcc, s12, v130
	s_mov_b64 s[12:13], 0x4800
	s_nop 0
	v_addc_co_u32_e32 v135, vcc, 0, v131, vcc
	global_store_dwordx4 v[134:135], v[62:65], off sc1
	global_store_dwordx4 v[132:133], v[58:61], off offset:16 sc1
	v_lshl_add_u64 v[132:133], v[130:131], 0, s[12:13]
	global_store_dwordx4 v[134:135], v[46:49], off offset:2048 sc1
	global_store_dwordx4 v[132:133], v[42:45], off offset:16 sc1
	s_mov_b64 s[12:13], 0x5000
	v_add_co_u32_e32 v134, vcc, 0x5000, v130
	v_lshl_add_u64 v[132:133], v[130:131], 0, s[12:13]
	s_nop 0
	v_addc_co_u32_e32 v135, vcc, 0, v131, vcc
	s_mov_b64 s[12:13], 0x5800
	global_store_dwordx4 v[134:135], v[30:33], off sc1
	global_store_dwordx4 v[132:133], v[26:29], off offset:16 sc1
	v_lshl_add_u64 v[130:131], v[130:131], 0, s[12:13]
	global_store_dwordx4 v[134:135], v[14:17], off offset:2048 sc1
	global_store_dwordx4 v[130:131], v[10:13], off offset:16 sc1

; __device__ __forceinline__ unsigned cvt_pk_bf16(float lo, float hi) { unsigned r; asm volatile("v_cvt_pk_bf16_f32 %0, %1, %2" : "=v"(r) : "v"(lo), "v"(hi)); return r; }
;     __device__ __forceinline__ void operator()(const f32x4 (&acc)[2][2][4][2], const Unit& u, int wr, int wc, int fr, int fq) const {
;     ...
;                 for (int m = 0; m < 4; ++m) { const int row = row0 + ai * HALF + m * 16; bf16_t* rowp = O + (size_t)row * ldc + col0;
;                     f32x4 c0 = {1.f, 1.f, 1.f, 1.f}, c1 = c0, s0 = {0.f, 0.f, 0.f, 0.f}, s1 = s0;
;                     if (rot) { const float* cp = G + (size_t)row * 8; c0 = *(const f32x4*)cp; c1 = *(const f32x4*)(cp + 4); s0 = *(const f32x4*)(cp + 131072); s1 = *(const f32x4*)(cp + 131072 + 4); }
; #pragma unroll
;                     for (int bj = 0; bj < 2; ++bj) { f32x4 v0 = acc[ai][bj][m][0], v1 = acc[ai][bj][m][1];
;                         if (rot) { f32x4 q0, q1;
; #pragma unroll
;                             for (int e = 0; e < 4; ++e) { q0[e] = __shfl_xor(v0[e], 16); q1[e] = __shfl_xor(v1[e], 16); }
;                             if (fq < 2) { v0 = v0 * c0 + sg * q0 * s0; v1 = v1 * c1 + sg * q1 * s1; } }
;                         u32x4 w; w.x = cvt_pk_bf16(v0[0], v0[1]); w.y = cvt_pk_bf16(v0[2], v0[3]); w.z = cvt_pk_bf16(v1[0], v1[1]); w.w = cvt_pk_bf16(v1[2], v1[3]);
;                         *(u32x4*)(rowp + bj * HALF) = w; } }
.LBB0_343:
	s_waitcnt lgkmcnt(0)
	v_mul_lo_u32 v176, s45, v170
	v_mul_lo_u32 v171, s44, v171
	v_mad_u64_u32 v[174:175], s[12:13], s44, v170, 0
	v_lshl_or_b32 v172, s73, 8, v200
	v_add3_u32 v175, v175, v171, v176
	v_ashrrev_i32_e32 v173, 31, v172
	v_lshl_add_u64 v[174:175], v[174:175], 1, s[8:9]
	v_lshl_add_u64 v[174:175], v[172:173], 1, v[174:175]
	s_and_b64 vcc, exec, s[42:43]
	v_cvt_pk_bf16_f32 v126, v126, v127
	v_cvt_pk_bf16_f32 v127, v128, v129
	v_cvt_pk_bf16_f32 v128, v122, v123
	v_cvt_pk_bf16_f32 v129, v124, v125
	global_store_dwordx4 v[174:175], v[126:129], off sc1
	s_cbranch_vccnz .LBB0_347
	v_and_b32_e32 v123, 64, v198
	v_xor_b32_e32 v122, 16, v198
	v_add_u32_e32 v123, 64, v123
	v_cmp_lt_i32_e32 vcc, v122, v123
	s_nop 1
	v_cndmask_b32_e32 v122, v198, v122, vcc
	v_lshlrev_b32_e32 v125, 2, v122
	ds_bpermute_b32 v126, v125, v118
	ds_bpermute_b32 v122, v125, v114
	ds_bpermute_b32 v127, v125, v119
	ds_bpermute_b32 v123, v125, v115
	ds_bpermute_b32 v128, v125, v120
	ds_bpermute_b32 v124, v125, v116
	ds_bpermute_b32 v129, v125, v121
	ds_bpermute_b32 v125, v125, v117
	s_and_saveexec_b64 s[12:13], s[38:39]
	s_cbranch_execz .LBB0_346
	s_waitcnt lgkmcnt(0)
	v_pk_mul_f32 v[128:129], v[150:151], v[128:129]
	v_pk_mul_f32 v[126:127], v[148:149], v[126:127]
	v_pk_mul_f32 v[124:125], v[150:151], v[124:125]
	v_pk_mul_f32 v[122:123], v[148:149], v[122:123]
	s_waitcnt vmcnt(0)
	v_pk_mul_f32 v[128:129], v[140:141], v[128:129]
	v_pk_mul_f32 v[126:127], v[138:139], v[126:127]
	v_pk_mul_f32 v[124:125], v[144:145], v[124:125]
	v_pk_mul_f32 v[122:123], v[142:143], v[122:123]
	v_pk_fma_f32 v[120:121], v[120:121], v[136:137], v[128:129]
	v_pk_fma_f32 v[118:119], v[118:119], v[134:135], v[126:127]
	v_pk_fma_f32 v[116:117], v[116:117], v[132:133], v[124:125]
	v_pk_fma_f32 v[114:115], v[114:115], v[130:131], v[122:123]

; __device__ __forceinline__ unsigned cvt_pk_bf16(float lo, float hi) { unsigned r; asm volatile("v_cvt_pk_bf16_f32 %0, %1, %2" : "=v"(r) : "v"(lo), "v"(hi)); return r; }
;     __device__ __forceinline__ void operator()(const f32x4 (&acc)[2][2][4][2], const Unit& u, int wr, int wc, int fr, int fq) const {
;     ...
;                 for (int m = 0; m < 4; ++m) { const int row = row0 + ai * HALF + m * 16; bf16_t* rowp = O + (size_t)row * ldc + col0;
;                     f32x4 c0 = {1.f, 1.f, 1.f, 1.f}, c1 = c0, s0 = {0.f, 0.f, 0.f, 0.f}, s1 = s0;
;                     if (rot) { const float* cp = G + (size_t)row * 8; c0 = *(const f32x4*)cp; c1 = *(const f32x4*)(cp + 4); s0 = *(const f32x4*)(cp + 131072); s1 = *(const f32x4*)(cp + 131072 + 4); }
; #pragma unroll
;                     for (int bj = 0; bj < 2; ++bj) { f32x4 v0 = acc[ai][bj][m][0], v1 = acc[ai][bj][m][1];
;                         if (rot) { f32x4 q0, q1;
; #pragma unroll
;                             for (int e = 0; e < 4; ++e) { q0[e] = __shfl_xor(v0[e], 16); q1[e] = __shfl_xor(v1[e], 16); }
;                             if (fq < 2) { v0 = v0 * c0 + sg * q0 * s0; v1 = v1 * c1 + sg * q1 * s1; } }
;                         u32x4 w; w.x = cvt_pk_bf16(v0[0], v0[1]); w.y = cvt_pk_bf16(v0[2], v0[3]); w.z = cvt_pk_bf16(v1[0], v1[1]); w.w = cvt_pk_bf16(v1[2], v1[3]);
;                         *(u32x4*)(rowp + bj * HALF) = w; } }
.LBB0_347:
	s_waitcnt vmcnt(0)
	v_or_b32_e32 v130, 16, v170
	s_and_b64 vcc, exec, s[42:43]
	v_ashrrev_i32_e32 v131, 31, v130
	v_cvt_pk_bf16_f32 v118, v118, v119
	v_cvt_pk_bf16_f32 v119, v120, v121
	v_cvt_pk_bf16_f32 v120, v114, v115
	v_cvt_pk_bf16_f32 v121, v116, v117
	global_store_dwordx4 v[174:175], v[118:121], off offset:256 sc1
	s_cbranch_vccnz .LBB0_349
	v_lshlrev_b64 v[114:115], 5, v[130:131]
	s_waitcnt lgkmcnt(4)
	v_lshl_add_u64 v[122:123], s[46:47], 0, v[114:115]
	v_lshl_add_u64 v[126:127], v[122:123], 0, s[96:97]
	global_load_dwordx4 v[118:121], v[122:123], off
	global_load_dwordx4 v[114:117], v[122:123], off offset:16
	v_add_co_u32_e32 v122, vcc, 0x80000, v122
	s_nop 1
	v_addc_co_u32_e32 v123, vcc, 0, v123, vcc
	s_waitcnt lgkmcnt(0)
	global_load_dwordx4 v[122:125], v[122:123], off
	s_nop 0
	global_load_dwordx4 v[126:129], v[126:127], off offset:16
	s_and_b64 vcc, exec, s[42:43]
	s_cbranch_vccz .LBB0_350
	s_branch .LBB0_353

; __device__ __forceinline__ unsigned cvt_pk_bf16(float lo, float hi) { unsigned r; asm volatile("v_cvt_pk_bf16_f32 %0, %1, %2" : "=v"(r) : "v"(lo), "v"(hi)); return r; }
;     __device__ __forceinline__ void operator()(const f32x4 (&acc)[2][2][4][2], const Unit& u, int wr, int wc, int fr, int fq) const {
;     ...
;                 for (int m = 0; m < 4; ++m) { const int row = row0 + ai * HALF + m * 16; bf16_t* rowp = O + (size_t)row * ldc + col0;
;                     f32x4 c0 = {1.f, 1.f, 1.f, 1.f}, c1 = c0, s0 = {0.f, 0.f, 0.f, 0.f}, s1 = s0;
;                     if (rot) { const float* cp = G + (size_t)row * 8; c0 = *(const f32x4*)cp; c1 = *(const f32x4*)(cp + 4); s0 = *(const f32x4*)(cp + 131072); s1 = *(const f32x4*)(cp + 131072 + 4); }
; #pragma unroll
;                     for (int bj = 0; bj < 2; ++bj) { f32x4 v0 = acc[ai][bj][m][0], v1 = acc[ai][bj][m][1];
;                         if (rot) { f32x4 q0, q1;
; #pragma unroll
;                             for (int e = 0; e < 4; ++e) { q0[e] = __shfl_xor(v0[e], 16); q1[e] = __shfl_xor(v1[e], 16); }
;                             if (fq < 2) { v0 = v0 * c0 + sg * q0 * s0; v1 = v1 * c1 + sg * q1 * s1; } }
;                         u32x4 w; w.x = cvt_pk_bf16(v0[0], v0[1]); w.y = cvt_pk_bf16(v0[2], v0[3]); w.z = cvt_pk_bf16(v1[0], v1[1]); w.w = cvt_pk_bf16(v1[2], v1[3]);
;                         *(u32x4*)(rowp + bj * HALF) = w; } }
.LBB0_353:
	s_waitcnt lgkmcnt(6)
	v_mul_lo_u32 v132, s45, v130
	s_waitcnt lgkmcnt(4)
	v_mul_lo_u32 v133, s44, v131
	v_mad_u64_u32 v[130:131], s[12:13], s44, v130, 0
	v_add3_u32 v131, v131, v133, v132
	v_lshl_add_u64 v[130:131], v[130:131], 1, s[8:9]
	v_lshl_add_u64 v[130:131], v[172:173], 1, v[130:131]
	s_and_b64 vcc, exec, s[42:43]
	v_cvt_pk_bf16_f32 v110, v110, v111
	v_cvt_pk_bf16_f32 v111, v112, v113
	v_cvt_pk_bf16_f32 v112, v106, v107
	v_cvt_pk_bf16_f32 v113, v108, v109
	global_store_dwordx4 v[130:131], v[110:113], off sc1
	s_cbranch_vccnz .LBB0_357
	v_and_b32_e32 v107, 64, v198
	v_xor_b32_e32 v106, 16, v198
	v_add_u32_e32 v107, 64, v107
	v_cmp_lt_i32_e32 vcc, v106, v107
	s_nop 1
	v_cndmask_b32_e32 v106, v198, v106, vcc
	v_lshlrev_b32_e32 v109, 2, v106
	ds_bpermute_b32 v110, v109, v102
	ds_bpermute_b32 v106, v109, v98
	ds_bpermute_b32 v111, v109, v103
	ds_bpermute_b32 v107, v109, v99
	ds_bpermute_b32 v112, v109, v104
	ds_bpermute_b32 v108, v109, v100
	ds_bpermute_b32 v113, v109, v105
	ds_bpermute_b32 v109, v109, v101
	s_and_saveexec_b64 s[12:13], s[38:39]
	s_cbranch_execz .LBB0_356
	s_waitcnt lgkmcnt(1)
	v_pk_mul_f32 v[112:113], v[150:151], v[112:113]
	v_pk_mul_f32 v[110:111], v[148:149], v[110:111]
	s_waitcnt lgkmcnt(0)
	v_pk_mul_f32 v[108:109], v[150:151], v[108:109]
	v_pk_mul_f32 v[106:107], v[148:149], v[106:107]
	s_waitcnt vmcnt(2)
	v_pk_mul_f32 v[112:113], v[124:125], v[112:113]
	v_pk_mul_f32 v[110:111], v[122:123], v[110:111]
	s_waitcnt vmcnt(1)
	v_pk_mul_f32 v[108:109], v[128:129], v[108:109]
	v_pk_mul_f32 v[106:107], v[126:127], v[106:107]
	v_pk_fma_f32 v[104:105], v[104:105], v[120:121], v[112:113]
	v_pk_fma_f32 v[102:103], v[102:103], v[118:119], v[110:111]
	v_pk_fma_f32 v[100:101], v[100:101], v[116:117], v[108:109]
	v_pk_fma_f32 v[98:99], v[98:99], v[114:115], v[106:107]

; __device__ __forceinline__ unsigned cvt_pk_bf16(float lo, float hi) { unsigned r; asm volatile("v_cvt_pk_bf16_f32 %0, %1, %2" : "=v"(r) : "v"(lo), "v"(hi)); return r; }
;     __device__ __forceinline__ void operator()(const f32x4 (&acc)[2][2][4][2], const Unit& u, int wr, int wc, int fr, int fq) const {
;     ...
;                 for (int m = 0; m < 4; ++m) { const int row = row0 + ai * HALF + m * 16; bf16_t* rowp = O + (size_t)row * ldc + col0;
;                     f32x4 c0 = {1.f, 1.f, 1.f, 1.f}, c1 = c0, s0 = {0.f, 0.f, 0.f, 0.f}, s1 = s0;
;                     if (rot) { const float* cp = G + (size_t)row * 8; c0 = *(const f32x4*)cp; c1 = *(const f32x4*)(cp + 4); s0 = *(const f32x4*)(cp + 131072); s1 = *(const f32x4*)(cp + 131072 + 4); }
; #pragma unroll
;                     for (int bj = 0; bj < 2; ++bj) { f32x4 v0 = acc[ai][bj][m][0], v1 = acc[ai][bj][m][1];
;                         if (rot) { f32x4 q0, q1;
; #pragma unroll
;                             for (int e = 0; e < 4; ++e) { q0[e] = __shfl_xor(v0[e], 16); q1[e] = __shfl_xor(v1[e], 16); }
;                             if (fq < 2) { v0 = v0 * c0 + sg * q0 * s0; v1 = v1 * c1 + sg * q1 * s1; } }
;                         u32x4 w; w.x = cvt_pk_bf16(v0[0], v0[1]); w.y = cvt_pk_bf16(v0[2], v0[3]); w.z = cvt_pk_bf16(v1[0], v1[1]); w.w = cvt_pk_bf16(v1[2], v1[3]);
;                         *(u32x4*)(rowp + bj * HALF) = w; } }
.LBB0_357:
	s_waitcnt vmcnt(3)
	v_or_b32_e32 v114, 32, v170
	s_and_b64 vcc, exec, s[42:43]
	v_ashrrev_i32_e32 v115, 31, v114
	v_cvt_pk_bf16_f32 v102, v102, v103
	v_cvt_pk_bf16_f32 v103, v104, v105
	v_cvt_pk_bf16_f32 v104, v98, v99
	v_cvt_pk_bf16_f32 v105, v100, v101
	global_store_dwordx4 v[130:131], v[102:105], off offset:256 sc1
	s_cbranch_vccnz .LBB0_359
	v_lshlrev_b64 v[98:99], 5, v[114:115]
	s_waitcnt lgkmcnt(4)
	v_lshl_add_u64 v[106:107], s[46:47], 0, v[98:99]
	v_lshl_add_u64 v[110:111], v[106:107], 0, s[96:97]
	global_load_dwordx4 v[102:105], v[106:107], off
	global_load_dwordx4 v[98:101], v[106:107], off offset:16
	v_add_co_u32_e32 v106, vcc, 0x80000, v106
	s_nop 1
	v_addc_co_u32_e32 v107, vcc, 0, v107, vcc
	s_waitcnt lgkmcnt(0)
	global_load_dwordx4 v[106:109], v[106:107], off
	s_nop 0
	global_load_dwordx4 v[110:113], v[110:111], off offset:16
	s_and_b64 vcc, exec, s[42:43]
	s_cbranch_vccz .LBB0_360
	s_branch .LBB0_363

; __device__ __forceinline__ unsigned cvt_pk_bf16(float lo, float hi) { unsigned r; asm volatile("v_cvt_pk_bf16_f32 %0, %1, %2" : "=v"(r) : "v"(lo), "v"(hi)); return r; }
;     __device__ __forceinline__ void operator()(const f32x4 (&acc)[2][2][4][2], const Unit& u, int wr, int wc, int fr, int fq) const {
;     ...
;                 for (int m = 0; m < 4; ++m) { const int row = row0 + ai * HALF + m * 16; bf16_t* rowp = O + (size_t)row * ldc + col0;
;                     f32x4 c0 = {1.f, 1.f, 1.f, 1.f}, c1 = c0, s0 = {0.f, 0.f, 0.f, 0.f}, s1 = s0;
;                     if (rot) { const float* cp = G + (size_t)row * 8; c0 = *(const f32x4*)cp; c1 = *(const f32x4*)(cp + 4); s0 = *(const f32x4*)(cp + 131072); s1 = *(const f32x4*)(cp + 131072 + 4); }
; #pragma unroll
;                     for (int bj = 0; bj < 2; ++bj) { f32x4 v0 = acc[ai][bj][m][0], v1 = acc[ai][bj][m][1];
;                         if (rot) { f32x4 q0, q1;
; #pragma unroll
;                             for (int e = 0; e < 4; ++e) { q0[e] = __shfl_xor(v0[e], 16); q1[e] = __shfl_xor(v1[e], 16); }
;                             if (fq < 2) { v0 = v0 * c0 + sg * q0 * s0; v1 = v1 * c1 + sg * q1 * s1; } }
;                         u32x4 w; w.x = cvt_pk_bf16(v0[0], v0[1]); w.y = cvt_pk_bf16(v0[2], v0[3]); w.z = cvt_pk_bf16(v1[0], v1[1]); w.w = cvt_pk_bf16(v1[2], v1[3]);
;                         *(u32x4*)(rowp + bj * HALF) = w; } }
.LBB0_363:
	s_waitcnt lgkmcnt(6)
	v_mul_lo_u32 v116, s45, v114
	s_waitcnt lgkmcnt(4)
	v_mul_lo_u32 v117, s44, v115
	v_mad_u64_u32 v[114:115], s[12:13], s44, v114, 0
	v_add3_u32 v115, v115, v117, v116
	v_lshl_add_u64 v[114:115], v[114:115], 1, s[8:9]
	v_lshl_add_u64 v[114:115], v[172:173], 1, v[114:115]
	s_and_b64 vcc, exec, s[42:43]
	v_cvt_pk_bf16_f32 v94, v94, v95
	v_cvt_pk_bf16_f32 v95, v96, v97
	v_cvt_pk_bf16_f32 v96, v90, v91
	v_cvt_pk_bf16_f32 v97, v92, v93
	global_store_dwordx4 v[114:115], v[94:97], off sc1
	s_cbranch_vccnz .LBB0_367
	v_and_b32_e32 v91, 64, v198
	v_xor_b32_e32 v90, 16, v198
	v_add_u32_e32 v91, 64, v91
	v_cmp_lt_i32_e32 vcc, v90, v91
	s_nop 1
	v_cndmask_b32_e32 v90, v198, v90, vcc
	v_lshlrev_b32_e32 v93, 2, v90
	ds_bpermute_b32 v94, v93, v86
	ds_bpermute_b32 v90, v93, v82
	ds_bpermute_b32 v95, v93, v87
	ds_bpermute_b32 v91, v93, v83
	ds_bpermute_b32 v96, v93, v88
	ds_bpermute_b32 v92, v93, v84
	ds_bpermute_b32 v97, v93, v89
	ds_bpermute_b32 v93, v93, v85
	s_and_saveexec_b64 s[12:13], s[38:39]
	s_cbranch_execz .LBB0_366
	s_waitcnt lgkmcnt(1)
	v_pk_mul_f32 v[96:97], v[150:151], v[96:97]
	v_pk_mul_f32 v[94:95], v[148:149], v[94:95]
	s_waitcnt lgkmcnt(0)
	v_pk_mul_f32 v[92:93], v[150:151], v[92:93]
	v_pk_mul_f32 v[90:91], v[148:149], v[90:91]
	s_waitcnt vmcnt(2)
	v_pk_mul_f32 v[96:97], v[108:109], v[96:97]
	v_pk_mul_f32 v[94:95], v[106:107], v[94:95]
	s_waitcnt vmcnt(1)
	v_pk_mul_f32 v[92:93], v[112:113], v[92:93]
	v_pk_mul_f32 v[90:91], v[110:111], v[90:91]
	v_pk_fma_f32 v[88:89], v[88:89], v[104:105], v[96:97]
	v_pk_fma_f32 v[86:87], v[86:87], v[102:103], v[94:95]
	v_pk_fma_f32 v[84:85], v[84:85], v[100:101], v[92:93]
	v_pk_fma_f32 v[82:83], v[82:83], v[98:99], v[90:91]

; __device__ __forceinline__ unsigned cvt_pk_bf16(float lo, float hi) { unsigned r; asm volatile("v_cvt_pk_bf16_f32 %0, %1, %2" : "=v"(r) : "v"(lo), "v"(hi)); return r; }
;     __device__ __forceinline__ void operator()(const f32x4 (&acc)[2][2][4][2], const Unit& u, int wr, int wc, int fr, int fq) const {
;     ...
;                 for (int m = 0; m < 4; ++m) { const int row = row0 + ai * HALF + m * 16; bf16_t* rowp = O + (size_t)row * ldc + col0;
;                     f32x4 c0 = {1.f, 1.f, 1.f, 1.f}, c1 = c0, s0 = {0.f, 0.f, 0.f, 0.f}, s1 = s0;
;                     if (rot) { const float* cp = G + (size_t)row * 8; c0 = *(const f32x4*)cp; c1 = *(const f32x4*)(cp + 4); s0 = *(const f32x4*)(cp + 131072); s1 = *(const f32x4*)(cp + 131072 + 4); }
; #pragma unroll
;                     for (int bj = 0; bj < 2; ++bj) { f32x4 v0 = acc[ai][bj][m][0], v1 = acc[ai][bj][m][1];
;                         if (rot) { f32x4 q0, q1;
; #pragma unroll
;                             for (int e = 0; e < 4; ++e) { q0[e] = __shfl_xor(v0[e], 16); q1[e] = __shfl_xor(v1[e], 16); }
;                             if (fq < 2) { v0 = v0 * c0 + sg * q0 * s0; v1 = v1 * c1 + sg * q1 * s1; } }
;                         u32x4 w; w.x = cvt_pk_bf16(v0[0], v0[1]); w.y = cvt_pk_bf16(v0[2], v0[3]); w.z = cvt_pk_bf16(v1[0], v1[1]); w.w = cvt_pk_bf16(v1[2], v1[3]);
;                         *(u32x4*)(rowp + bj * HALF) = w; } }
.LBB0_367:
	s_waitcnt vmcnt(3)
	v_or_b32_e32 v98, 48, v170
	s_and_b64 vcc, exec, s[42:43]
	v_ashrrev_i32_e32 v99, 31, v98
	v_cvt_pk_bf16_f32 v86, v86, v87
	v_cvt_pk_bf16_f32 v87, v88, v89
	v_cvt_pk_bf16_f32 v88, v82, v83
	v_cvt_pk_bf16_f32 v89, v84, v85
	global_store_dwordx4 v[114:115], v[86:89], off offset:256 sc1
	s_cbranch_vccnz .LBB0_369
	v_lshlrev_b64 v[82:83], 5, v[98:99]
	s_waitcnt lgkmcnt(4)
	v_lshl_add_u64 v[90:91], s[46:47], 0, v[82:83]
	v_lshl_add_u64 v[94:95], v[90:91], 0, s[96:97]
	global_load_dwordx4 v[86:89], v[90:91], off
	global_load_dwordx4 v[82:85], v[90:91], off offset:16
	v_add_co_u32_e32 v90, vcc, 0x80000, v90
	s_nop 1
	v_addc_co_u32_e32 v91, vcc, 0, v91, vcc
	s_waitcnt lgkmcnt(0)
	global_load_dwordx4 v[90:93], v[90:91], off
	s_nop 0
	global_load_dwordx4 v[94:97], v[94:95], off offset:16
	s_and_b64 vcc, exec, s[42:43]
	s_cbranch_vccz .LBB0_370
	s_branch .LBB0_373

; __device__ __forceinline__ unsigned cvt_pk_bf16(float lo, float hi) { unsigned r; asm volatile("v_cvt_pk_bf16_f32 %0, %1, %2" : "=v"(r) : "v"(lo), "v"(hi)); return r; }
;     __device__ __forceinline__ void operator()(const f32x4 (&acc)[2][2][4][2], const Unit& u, int wr, int wc, int fr, int fq) const {
;     ...
;                 for (int m = 0; m < 4; ++m) { const int row = row0 + ai * HALF + m * 16; bf16_t* rowp = O + (size_t)row * ldc + col0;
;                     f32x4 c0 = {1.f, 1.f, 1.f, 1.f}, c1 = c0, s0 = {0.f, 0.f, 0.f, 0.f}, s1 = s0;
;                     if (rot) { const float* cp = G + (size_t)row * 8; c0 = *(const f32x4*)cp; c1 = *(const f32x4*)(cp + 4); s0 = *(const f32x4*)(cp + 131072); s1 = *(const f32x4*)(cp + 131072 + 4); }
; #pragma unroll
;                     for (int bj = 0; bj < 2; ++bj) { f32x4 v0 = acc[ai][bj][m][0], v1 = acc[ai][bj][m][1];
;                         if (rot) { f32x4 q0, q1;
; #pragma unroll
;                             for (int e = 0; e < 4; ++e) { q0[e] = __shfl_xor(v0[e], 16); q1[e] = __shfl_xor(v1[e], 16); }
;                             if (fq < 2) { v0 = v0 * c0 + sg * q0 * s0; v1 = v1 * c1 + sg * q1 * s1; } }
;                         u32x4 w; w.x = cvt_pk_bf16(v0[0], v0[1]); w.y = cvt_pk_bf16(v0[2], v0[3]); w.z = cvt_pk_bf16(v1[0], v1[1]); w.w = cvt_pk_bf16(v1[2], v1[3]);
;                         *(u32x4*)(rowp + bj * HALF) = w; } }
.LBB0_373:
	s_waitcnt lgkmcnt(6)
	v_mul_lo_u32 v100, s45, v98
	s_waitcnt lgkmcnt(4)
	v_mul_lo_u32 v101, s44, v99
	v_mad_u64_u32 v[98:99], s[12:13], s44, v98, 0
	v_add3_u32 v99, v99, v101, v100
	v_lshl_add_u64 v[98:99], v[98:99], 1, s[8:9]
	v_lshl_add_u64 v[98:99], v[172:173], 1, v[98:99]
	s_and_b64 vcc, exec, s[42:43]
	v_cvt_pk_bf16_f32 v78, v78, v79
	v_cvt_pk_bf16_f32 v79, v80, v81
	v_cvt_pk_bf16_f32 v80, v74, v75
	v_cvt_pk_bf16_f32 v81, v76, v77
	global_store_dwordx4 v[98:99], v[78:81], off sc1
	s_cbranch_vccnz .LBB0_377
	v_and_b32_e32 v75, 64, v198
	v_xor_b32_e32 v74, 16, v198
	v_add_u32_e32 v75, 64, v75
	v_cmp_lt_i32_e32 vcc, v74, v75
	s_nop 1
	v_cndmask_b32_e32 v74, v198, v74, vcc
	v_lshlrev_b32_e32 v77, 2, v74
	ds_bpermute_b32 v78, v77, v70
	ds_bpermute_b32 v74, v77, v66
	ds_bpermute_b32 v79, v77, v71
	ds_bpermute_b32 v75, v77, v67
	ds_bpermute_b32 v80, v77, v72
	ds_bpermute_b32 v76, v77, v68
	ds_bpermute_b32 v81, v77, v73
	ds_bpermute_b32 v77, v77, v69
	s_and_saveexec_b64 s[12:13], s[38:39]
	s_cbranch_execz .LBB0_376
	s_waitcnt lgkmcnt(1)
	v_pk_mul_f32 v[80:81], v[150:151], v[80:81]
	v_pk_mul_f32 v[78:79], v[148:149], v[78:79]
	s_waitcnt lgkmcnt(0)
	v_pk_mul_f32 v[76:77], v[150:151], v[76:77]
	v_pk_mul_f32 v[74:75], v[148:149], v[74:75]
	s_waitcnt vmcnt(2)
	v_pk_mul_f32 v[80:81], v[92:93], v[80:81]
	v_pk_mul_f32 v[78:79], v[90:91], v[78:79]
	s_waitcnt vmcnt(1)
	v_pk_mul_f32 v[76:77], v[96:97], v[76:77]
	v_pk_mul_f32 v[74:75], v[94:95], v[74:75]
	v_pk_fma_f32 v[72:73], v[72:73], v[88:89], v[80:81]
	v_pk_fma_f32 v[70:71], v[70:71], v[86:87], v[78:79]
	v_pk_fma_f32 v[68:69], v[68:69], v[84:85], v[76:77]
	v_pk_fma_f32 v[66:67], v[66:67], v[82:83], v[74:75]

; __device__ __forceinline__ unsigned cvt_pk_bf16(float lo, float hi) { unsigned r; asm volatile("v_cvt_pk_bf16_f32 %0, %1, %2" : "=v"(r) : "v"(lo), "v"(hi)); return r; }
;     __device__ __forceinline__ void operator()(const f32x4 (&acc)[2][2][4][2], const Unit& u, int wr, int wc, int fr, int fq) const {
;     ...
;                 for (int m = 0; m < 4; ++m) { const int row = row0 + ai * HALF + m * 16; bf16_t* rowp = O + (size_t)row * ldc + col0;
;                     f32x4 c0 = {1.f, 1.f, 1.f, 1.f}, c1 = c0, s0 = {0.f, 0.f, 0.f, 0.f}, s1 = s0;
;                     if (rot) { const float* cp = G + (size_t)row * 8; c0 = *(const f32x4*)cp; c1 = *(const f32x4*)(cp + 4); s0 = *(const f32x4*)(cp + 131072); s1 = *(const f32x4*)(cp + 131072 + 4); }
; #pragma unroll
;                     for (int bj = 0; bj < 2; ++bj) { f32x4 v0 = acc[ai][bj][m][0], v1 = acc[ai][bj][m][1];
;                         if (rot) { f32x4 q0, q1;
; #pragma unroll
;                             for (int e = 0; e < 4; ++e) { q0[e] = __shfl_xor(v0[e], 16); q1[e] = __shfl_xor(v1[e], 16); }
;                             if (fq < 2) { v0 = v0 * c0 + sg * q0 * s0; v1 = v1 * c1 + sg * q1 * s1; } }
;                         u32x4 w; w.x = cvt_pk_bf16(v0[0], v0[1]); w.y = cvt_pk_bf16(v0[2], v0[3]); w.z = cvt_pk_bf16(v1[0], v1[1]); w.w = cvt_pk_bf16(v1[2], v1[3]);
;                         *(u32x4*)(rowp + bj * HALF) = w; } }
.LBB0_377:
	s_waitcnt vmcnt(3)
	v_add_u32_e32 v82, 0x80, v170
	s_and_b64 vcc, exec, s[42:43]
	v_ashrrev_i32_e32 v83, 31, v82
	v_cvt_pk_bf16_f32 v70, v70, v71
	v_cvt_pk_bf16_f32 v71, v72, v73
	v_cvt_pk_bf16_f32 v72, v66, v67
	v_cvt_pk_bf16_f32 v73, v68, v69
	global_store_dwordx4 v[98:99], v[70:73], off offset:256 sc1
	s_cbranch_vccnz .LBB0_379
	v_lshlrev_b64 v[66:67], 5, v[82:83]
	s_waitcnt lgkmcnt(4)
	v_lshl_add_u64 v[74:75], s[46:47], 0, v[66:67]
	v_lshl_add_u64 v[78:79], v[74:75], 0, s[96:97]
	global_load_dwordx4 v[70:73], v[74:75], off
	global_load_dwordx4 v[66:69], v[74:75], off offset:16
	v_add_co_u32_e32 v74, vcc, 0x80000, v74
	s_nop 1
	v_addc_co_u32_e32 v75, vcc, 0, v75, vcc
	s_waitcnt lgkmcnt(0)
	global_load_dwordx4 v[74:77], v[74:75], off
	s_nop 0
	global_load_dwordx4 v[78:81], v[78:79], off offset:16
	s_and_b64 vcc, exec, s[42:43]
	s_cbranch_vccz .LBB0_380
	s_branch .LBB0_383

; __device__ __forceinline__ unsigned cvt_pk_bf16(float lo, float hi) { unsigned r; asm volatile("v_cvt_pk_bf16_f32 %0, %1, %2" : "=v"(r) : "v"(lo), "v"(hi)); return r; }
;     __device__ __forceinline__ void operator()(const f32x4 (&acc)[2][2][4][2], const Unit& u, int wr, int wc, int fr, int fq) const {
;     ...
;                 for (int m = 0; m < 4; ++m) { const int row = row0 + ai * HALF + m * 16; bf16_t* rowp = O + (size_t)row * ldc + col0;
;                     f32x4 c0 = {1.f, 1.f, 1.f, 1.f}, c1 = c0, s0 = {0.f, 0.f, 0.f, 0.f}, s1 = s0;
;                     if (rot) { const float* cp = G + (size_t)row * 8; c0 = *(const f32x4*)cp; c1 = *(const f32x4*)(cp + 4); s0 = *(const f32x4*)(cp + 131072); s1 = *(const f32x4*)(cp + 131072 + 4); }
; #pragma unroll
;                     for (int bj = 0; bj < 2; ++bj) { f32x4 v0 = acc[ai][bj][m][0], v1 = acc[ai][bj][m][1];
;                         if (rot) { f32x4 q0, q1;
; #pragma unroll
;                             for (int e = 0; e < 4; ++e) { q0[e] = __shfl_xor(v0[e], 16); q1[e] = __shfl_xor(v1[e], 16); }
;                             if (fq < 2) { v0 = v0 * c0 + sg * q0 * s0; v1 = v1 * c1 + sg * q1 * s1; } }
;                         u32x4 w; w.x = cvt_pk_bf16(v0[0], v0[1]); w.y = cvt_pk_bf16(v0[2], v0[3]); w.z = cvt_pk_bf16(v1[0], v1[1]); w.w = cvt_pk_bf16(v1[2], v1[3]);
;                         *(u32x4*)(rowp + bj * HALF) = w; } }
.LBB0_383:
	s_waitcnt lgkmcnt(6)
	v_mul_lo_u32 v84, s45, v82
	s_waitcnt lgkmcnt(4)
	v_mul_lo_u32 v85, s44, v83
	v_mad_u64_u32 v[82:83], s[12:13], s44, v82, 0
	v_add3_u32 v83, v83, v85, v84
	v_lshl_add_u64 v[82:83], v[82:83], 1, s[8:9]
	v_lshl_add_u64 v[82:83], v[172:173], 1, v[82:83]
	s_and_b64 vcc, exec, s[42:43]
	v_cvt_pk_bf16_f32 v62, v62, v63
	v_cvt_pk_bf16_f32 v63, v64, v65
	v_cvt_pk_bf16_f32 v64, v58, v59
	v_cvt_pk_bf16_f32 v65, v60, v61
	global_store_dwordx4 v[82:83], v[62:65], off sc1
	s_cbranch_vccnz .LBB0_387
	v_and_b32_e32 v59, 64, v198
	v_xor_b32_e32 v58, 16, v198
	v_add_u32_e32 v59, 64, v59
	v_cmp_lt_i32_e32 vcc, v58, v59
	s_nop 1
	v_cndmask_b32_e32 v58, v198, v58, vcc
	v_lshlrev_b32_e32 v61, 2, v58
	ds_bpermute_b32 v62, v61, v54
	ds_bpermute_b32 v58, v61, v50
	ds_bpermute_b32 v63, v61, v55
	ds_bpermute_b32 v59, v61, v51
	ds_bpermute_b32 v64, v61, v56
	ds_bpermute_b32 v60, v61, v52
	ds_bpermute_b32 v65, v61, v57
	ds_bpermute_b32 v61, v61, v53
	s_and_saveexec_b64 s[12:13], s[38:39]
	s_cbranch_execz .LBB0_386
	s_waitcnt lgkmcnt(1)
	v_pk_mul_f32 v[64:65], v[150:151], v[64:65]
	v_pk_mul_f32 v[62:63], v[148:149], v[62:63]
	s_waitcnt lgkmcnt(0)
	v_pk_mul_f32 v[60:61], v[150:151], v[60:61]
	v_pk_mul_f32 v[58:59], v[148:149], v[58:59]
	s_waitcnt vmcnt(2)
	v_pk_mul_f32 v[64:65], v[76:77], v[64:65]
	v_pk_mul_f32 v[62:63], v[74:75], v[62:63]
	s_waitcnt vmcnt(1)
	v_pk_mul_f32 v[60:61], v[80:81], v[60:61]
	v_pk_mul_f32 v[58:59], v[78:79], v[58:59]
	v_pk_fma_f32 v[56:57], v[56:57], v[72:73], v[64:65]
	v_pk_fma_f32 v[54:55], v[54:55], v[70:71], v[62:63]
	v_pk_fma_f32 v[52:53], v[52:53], v[68:69], v[60:61]
	v_pk_fma_f32 v[50:51], v[50:51], v[66:67], v[58:59]

; __device__ __forceinline__ unsigned cvt_pk_bf16(float lo, float hi) { unsigned r; asm volatile("v_cvt_pk_bf16_f32 %0, %1, %2" : "=v"(r) : "v"(lo), "v"(hi)); return r; }
;     __device__ __forceinline__ void operator()(const f32x4 (&acc)[2][2][4][2], const Unit& u, int wr, int wc, int fr, int fq) const {
;     ...
;                 for (int m = 0; m < 4; ++m) { const int row = row0 + ai * HALF + m * 16; bf16_t* rowp = O + (size_t)row * ldc + col0;
;                     f32x4 c0 = {1.f, 1.f, 1.f, 1.f}, c1 = c0, s0 = {0.f, 0.f, 0.f, 0.f}, s1 = s0;
;                     if (rot) { const float* cp = G + (size_t)row * 8; c0 = *(const f32x4*)cp; c1 = *(const f32x4*)(cp + 4); s0 = *(const f32x4*)(cp + 131072); s1 = *(const f32x4*)(cp + 131072 + 4); }
; #pragma unroll
;                     for (int bj = 0; bj < 2; ++bj) { f32x4 v0 = acc[ai][bj][m][0], v1 = acc[ai][bj][m][1];
;                         if (rot) { f32x4 q0, q1;
; #pragma unroll
;                             for (int e = 0; e < 4; ++e) { q0[e] = __shfl_xor(v0[e], 16); q1[e] = __shfl_xor(v1[e], 16); }
;                             if (fq < 2) { v0 = v0 * c0 + sg * q0 * s0; v1 = v1 * c1 + sg * q1 * s1; } }
;                         u32x4 w; w.x = cvt_pk_bf16(v0[0], v0[1]); w.y = cvt_pk_bf16(v0[2], v0[3]); w.z = cvt_pk_bf16(v1[0], v1[1]); w.w = cvt_pk_bf16(v1[2], v1[3]);
;                         *(u32x4*)(rowp + bj * HALF) = w; } }
.LBB0_387:
	s_waitcnt vmcnt(3)
	v_add_u32_e32 v66, 0x90, v170
	s_and_b64 vcc, exec, s[42:43]
	v_ashrrev_i32_e32 v67, 31, v66
	v_cvt_pk_bf16_f32 v54, v54, v55
	v_cvt_pk_bf16_f32 v55, v56, v57
	v_cvt_pk_bf16_f32 v56, v50, v51
	v_cvt_pk_bf16_f32 v57, v52, v53
	global_store_dwordx4 v[82:83], v[54:57], off offset:256 sc1
	s_cbranch_vccnz .LBB0_389
	v_lshlrev_b64 v[50:51], 5, v[66:67]
	s_waitcnt lgkmcnt(4)
	v_lshl_add_u64 v[58:59], s[46:47], 0, v[50:51]
	v_lshl_add_u64 v[62:63], v[58:59], 0, s[96:97]
	global_load_dwordx4 v[54:57], v[58:59], off
	global_load_dwordx4 v[50:53], v[58:59], off offset:16
	v_add_co_u32_e32 v58, vcc, 0x80000, v58
	s_nop 1
	v_addc_co_u32_e32 v59, vcc, 0, v59, vcc
	s_waitcnt lgkmcnt(0)
	global_load_dwordx4 v[58:61], v[58:59], off
	s_nop 0
	global_load_dwordx4 v[62:65], v[62:63], off offset:16
	s_and_b64 vcc, exec, s[42:43]
	s_cbranch_vccz .LBB0_390
	s_branch .LBB0_393

; __device__ __forceinline__ unsigned cvt_pk_bf16(float lo, float hi) { unsigned r; asm volatile("v_cvt_pk_bf16_f32 %0, %1, %2" : "=v"(r) : "v"(lo), "v"(hi)); return r; }
;     __device__ __forceinline__ void operator()(const f32x4 (&acc)[2][2][4][2], const Unit& u, int wr, int wc, int fr, int fq) const {
;     ...
;                 for (int m = 0; m < 4; ++m) { const int row = row0 + ai * HALF + m * 16; bf16_t* rowp = O + (size_t)row * ldc + col0;
;                     f32x4 c0 = {1.f, 1.f, 1.f, 1.f}, c1 = c0, s0 = {0.f, 0.f, 0.f, 0.f}, s1 = s0;
;                     if (rot) { const float* cp = G + (size_t)row * 8; c0 = *(const f32x4*)cp; c1 = *(const f32x4*)(cp + 4); s0 = *(const f32x4*)(cp + 131072); s1 = *(const f32x4*)(cp + 131072 + 4); }
; #pragma unroll
;                     for (int bj = 0; bj < 2; ++bj) { f32x4 v0 = acc[ai][bj][m][0], v1 = acc[ai][bj][m][1];
;                         if (rot) { f32x4 q0, q1;
; #pragma unroll
;                             for (int e = 0; e < 4; ++e) { q0[e] = __shfl_xor(v0[e], 16); q1[e] = __shfl_xor(v1[e], 16); }
;                             if (fq < 2) { v0 = v0 * c0 + sg * q0 * s0; v1 = v1 * c1 + sg * q1 * s1; } }
;                         u32x4 w; w.x = cvt_pk_bf16(v0[0], v0[1]); w.y = cvt_pk_bf16(v0[2], v0[3]); w.z = cvt_pk_bf16(v1[0], v1[1]); w.w = cvt_pk_bf16(v1[2], v1[3]);
;                         *(u32x4*)(rowp + bj * HALF) = w; } }
.LBB0_393:
	s_waitcnt lgkmcnt(6)
	v_mul_lo_u32 v68, s45, v66
	s_waitcnt lgkmcnt(4)
	v_mul_lo_u32 v69, s44, v67
	v_mad_u64_u32 v[66:67], s[12:13], s44, v66, 0
	v_add3_u32 v67, v67, v69, v68
	v_lshl_add_u64 v[66:67], v[66:67], 1, s[8:9]
	v_lshl_add_u64 v[66:67], v[172:173], 1, v[66:67]
	s_and_b64 vcc, exec, s[42:43]
	v_cvt_pk_bf16_f32 v46, v46, v47
	v_cvt_pk_bf16_f32 v47, v48, v49
	v_cvt_pk_bf16_f32 v48, v42, v43
	v_cvt_pk_bf16_f32 v49, v44, v45
	global_store_dwordx4 v[66:67], v[46:49], off sc1
	s_cbranch_vccnz .LBB0_397
	v_and_b32_e32 v43, 64, v198
	v_xor_b32_e32 v42, 16, v198
	v_add_u32_e32 v43, 64, v43
	v_cmp_lt_i32_e32 vcc, v42, v43
	s_nop 1
	v_cndmask_b32_e32 v42, v198, v42, vcc
	v_lshlrev_b32_e32 v45, 2, v42
	ds_bpermute_b32 v46, v45, v38
	ds_bpermute_b32 v42, v45, v34
	ds_bpermute_b32 v47, v45, v39
	ds_bpermute_b32 v43, v45, v35
	ds_bpermute_b32 v48, v45, v40
	ds_bpermute_b32 v44, v45, v36
	ds_bpermute_b32 v49, v45, v41
	ds_bpermute_b32 v45, v45, v37
	s_and_saveexec_b64 s[12:13], s[38:39]
	s_cbranch_execz .LBB0_396
	s_waitcnt lgkmcnt(1)
	v_pk_mul_f32 v[48:49], v[150:151], v[48:49]
	v_pk_mul_f32 v[46:47], v[148:149], v[46:47]
	s_waitcnt lgkmcnt(0)
	v_pk_mul_f32 v[44:45], v[150:151], v[44:45]
	v_pk_mul_f32 v[42:43], v[148:149], v[42:43]
	s_waitcnt vmcnt(2)
	v_pk_mul_f32 v[48:49], v[60:61], v[48:49]
	v_pk_mul_f32 v[46:47], v[58:59], v[46:47]
	s_waitcnt vmcnt(1)
	v_pk_mul_f32 v[44:45], v[64:65], v[44:45]
	v_pk_mul_f32 v[42:43], v[62:63], v[42:43]
	v_pk_fma_f32 v[40:41], v[40:41], v[56:57], v[48:49]
	v_pk_fma_f32 v[38:39], v[38:39], v[54:55], v[46:47]
	v_pk_fma_f32 v[36:37], v[36:37], v[52:53], v[44:45]
	v_pk_fma_f32 v[34:35], v[34:35], v[50:51], v[42:43]

; __device__ __forceinline__ unsigned cvt_pk_bf16(float lo, float hi) { unsigned r; asm volatile("v_cvt_pk_bf16_f32 %0, %1, %2" : "=v"(r) : "v"(lo), "v"(hi)); return r; }
;     __device__ __forceinline__ void operator()(const f32x4 (&acc)[2][2][4][2], const Unit& u, int wr, int wc, int fr, int fq) const {
;     ...
;                 for (int m = 0; m < 4; ++m) { const int row = row0 + ai * HALF + m * 16; bf16_t* rowp = O + (size_t)row * ldc + col0;
;                     f32x4 c0 = {1.f, 1.f, 1.f, 1.f}, c1 = c0, s0 = {0.f, 0.f, 0.f, 0.f}, s1 = s0;
;                     if (rot) { const float* cp = G + (size_t)row * 8; c0 = *(const f32x4*)cp; c1 = *(const f32x4*)(cp + 4); s0 = *(const f32x4*)(cp + 131072); s1 = *(const f32x4*)(cp + 131072 + 4); }
; #pragma unroll
;                     for (int bj = 0; bj < 2; ++bj) { f32x4 v0 = acc[ai][bj][m][0], v1 = acc[ai][bj][m][1];
;                         if (rot) { f32x4 q0, q1;
; #pragma unroll
;                             for (int e = 0; e < 4; ++e) { q0[e] = __shfl_xor(v0[e], 16); q1[e] = __shfl_xor(v1[e], 16); }
;                             if (fq < 2) { v0 = v0 * c0 + sg * q0 * s0; v1 = v1 * c1 + sg * q1 * s1; } }
;                         u32x4 w; w.x = cvt_pk_bf16(v0[0], v0[1]); w.y = cvt_pk_bf16(v0[2], v0[3]); w.z = cvt_pk_bf16(v1[0], v1[1]); w.w = cvt_pk_bf16(v1[2], v1[3]);
;                         *(u32x4*)(rowp + bj * HALF) = w; } }
.LBB0_397:
	s_waitcnt vmcnt(3)
	v_add_u32_e32 v50, 0xa0, v170
	s_and_b64 vcc, exec, s[42:43]
	v_ashrrev_i32_e32 v51, 31, v50
	v_cvt_pk_bf16_f32 v38, v38, v39
	v_cvt_pk_bf16_f32 v39, v40, v41
	v_cvt_pk_bf16_f32 v40, v34, v35
	v_cvt_pk_bf16_f32 v41, v36, v37
	global_store_dwordx4 v[66:67], v[38:41], off offset:256 sc1
	s_cbranch_vccnz .LBB0_399
	v_lshlrev_b64 v[34:35], 5, v[50:51]
	s_waitcnt lgkmcnt(4)
	v_lshl_add_u64 v[42:43], s[46:47], 0, v[34:35]
	v_lshl_add_u64 v[46:47], v[42:43], 0, s[96:97]
	global_load_dwordx4 v[38:41], v[42:43], off
	global_load_dwordx4 v[34:37], v[42:43], off offset:16
	v_add_co_u32_e32 v42, vcc, 0x80000, v42
	s_nop 1
	v_addc_co_u32_e32 v43, vcc, 0, v43, vcc
	s_waitcnt lgkmcnt(0)
	global_load_dwordx4 v[42:45], v[42:43], off
	s_nop 0
	global_load_dwordx4 v[46:49], v[46:47], off offset:16
	s_and_b64 vcc, exec, s[42:43]
	s_cbranch_vccz .LBB0_400
	s_branch .LBB0_403

; __device__ __forceinline__ unsigned cvt_pk_bf16(float lo, float hi) { unsigned r; asm volatile("v_cvt_pk_bf16_f32 %0, %1, %2" : "=v"(r) : "v"(lo), "v"(hi)); return r; }
;     __device__ __forceinline__ void operator()(const f32x4 (&acc)[2][2][4][2], const Unit& u, int wr, int wc, int fr, int fq) const {
;     ...
;                 for (int m = 0; m < 4; ++m) { const int row = row0 + ai * HALF + m * 16; bf16_t* rowp = O + (size_t)row * ldc + col0;
;                     f32x4 c0 = {1.f, 1.f, 1.f, 1.f}, c1 = c0, s0 = {0.f, 0.f, 0.f, 0.f}, s1 = s0;
;                     if (rot) { const float* cp = G + (size_t)row * 8; c0 = *(const f32x4*)cp; c1 = *(const f32x4*)(cp + 4); s0 = *(const f32x4*)(cp + 131072); s1 = *(const f32x4*)(cp + 131072 + 4); }
; #pragma unroll
;                     for (int bj = 0; bj < 2; ++bj) { f32x4 v0 = acc[ai][bj][m][0], v1 = acc[ai][bj][m][1];
;                         if (rot) { f32x4 q0, q1;
; #pragma unroll
;                             for (int e = 0; e < 4; ++e) { q0[e] = __shfl_xor(v0[e], 16); q1[e] = __shfl_xor(v1[e], 16); }
;                             if (fq < 2) { v0 = v0 * c0 + sg * q0 * s0; v1 = v1 * c1 + sg * q1 * s1; } }
;                         u32x4 w; w.x = cvt_pk_bf16(v0[0], v0[1]); w.y = cvt_pk_bf16(v0[2], v0[3]); w.z = cvt_pk_bf16(v1[0], v1[1]); w.w = cvt_pk_bf16(v1[2], v1[3]);
;                         *(u32x4*)(rowp + bj * HALF) = w; } }
.LBB0_403:
	s_waitcnt lgkmcnt(6)
	v_mul_lo_u32 v52, s45, v50
	s_waitcnt lgkmcnt(4)
	v_mul_lo_u32 v53, s44, v51
	v_mad_u64_u32 v[50:51], s[12:13], s44, v50, 0
	v_add3_u32 v51, v51, v53, v52
	v_lshl_add_u64 v[50:51], v[50:51], 1, s[8:9]
	v_lshl_add_u64 v[50:51], v[172:173], 1, v[50:51]
	s_and_b64 vcc, exec, s[42:43]
	v_cvt_pk_bf16_f32 v30, v30, v31
	v_cvt_pk_bf16_f32 v31, v32, v33
	v_cvt_pk_bf16_f32 v32, v26, v27
	v_cvt_pk_bf16_f32 v33, v28, v29
	global_store_dwordx4 v[50:51], v[30:33], off sc1
	s_cbranch_vccnz .LBB0_407
	v_and_b32_e32 v27, 64, v198
	v_xor_b32_e32 v26, 16, v198
	v_add_u32_e32 v27, 64, v27
	v_cmp_lt_i32_e32 vcc, v26, v27
	s_nop 1
	v_cndmask_b32_e32 v26, v198, v26, vcc
	v_lshlrev_b32_e32 v29, 2, v26
	ds_bpermute_b32 v30, v29, v22
	ds_bpermute_b32 v26, v29, v18
	ds_bpermute_b32 v31, v29, v23
	ds_bpermute_b32 v27, v29, v19
	ds_bpermute_b32 v32, v29, v24
	ds_bpermute_b32 v28, v29, v20
	ds_bpermute_b32 v33, v29, v25
	ds_bpermute_b32 v29, v29, v21
	s_and_saveexec_b64 s[12:13], s[38:39]
	s_cbranch_execz .LBB0_406
	s_waitcnt lgkmcnt(1)
	v_pk_mul_f32 v[32:33], v[150:151], v[32:33]
	v_pk_mul_f32 v[30:31], v[148:149], v[30:31]
	s_waitcnt lgkmcnt(0)
	v_pk_mul_f32 v[28:29], v[150:151], v[28:29]
	v_pk_mul_f32 v[26:27], v[148:149], v[26:27]
	s_waitcnt vmcnt(2)
	v_pk_mul_f32 v[32:33], v[44:45], v[32:33]
	v_pk_mul_f32 v[30:31], v[42:43], v[30:31]
	s_waitcnt vmcnt(1)
	v_pk_mul_f32 v[28:29], v[48:49], v[28:29]
	v_pk_mul_f32 v[26:27], v[46:47], v[26:27]
	v_pk_fma_f32 v[24:25], v[24:25], v[40:41], v[32:33]
	v_pk_fma_f32 v[22:23], v[22:23], v[38:39], v[30:31]
	v_pk_fma_f32 v[20:21], v[20:21], v[36:37], v[28:29]
	v_pk_fma_f32 v[18:19], v[18:19], v[34:35], v[26:27]

; __device__ __forceinline__ unsigned cvt_pk_bf16(float lo, float hi) { unsigned r; asm volatile("v_cvt_pk_bf16_f32 %0, %1, %2" : "=v"(r) : "v"(lo), "v"(hi)); return r; }
;     __device__ __forceinline__ void operator()(const f32x4 (&acc)[2][2][4][2], const Unit& u, int wr, int wc, int fr, int fq) const {
;     ...
;                 for (int m = 0; m < 4; ++m) { const int row = row0 + ai * HALF + m * 16; bf16_t* rowp = O + (size_t)row * ldc + col0;
;                     f32x4 c0 = {1.f, 1.f, 1.f, 1.f}, c1 = c0, s0 = {0.f, 0.f, 0.f, 0.f}, s1 = s0;
;                     if (rot) { const float* cp = G + (size_t)row * 8; c0 = *(const f32x4*)cp; c1 = *(const f32x4*)(cp + 4); s0 = *(const f32x4*)(cp + 131072); s1 = *(const f32x4*)(cp + 131072 + 4); }
; #pragma unroll
;                     for (int bj = 0; bj < 2; ++bj) { f32x4 v0 = acc[ai][bj][m][0], v1 = acc[ai][bj][m][1];
;                         if (rot) { f32x4 q0, q1;
; #pragma unroll
;                             for (int e = 0; e < 4; ++e) { q0[e] = __shfl_xor(v0[e], 16); q1[e] = __shfl_xor(v1[e], 16); }
;                             if (fq < 2) { v0 = v0 * c0 + sg * q0 * s0; v1 = v1 * c1 + sg * q1 * s1; } }
;                         u32x4 w; w.x = cvt_pk_bf16(v0[0], v0[1]); w.y = cvt_pk_bf16(v0[2], v0[3]); w.z = cvt_pk_bf16(v1[0], v1[1]); w.w = cvt_pk_bf16(v1[2], v1[3]);
;                         *(u32x4*)(rowp + bj * HALF) = w; } }
.LBB0_407:
	s_waitcnt vmcnt(3)
	v_add_u32_e32 v34, 0xb0, v170
	s_and_b64 vcc, exec, s[42:43]
	v_ashrrev_i32_e32 v35, 31, v34
	v_cvt_pk_bf16_f32 v22, v22, v23
	v_cvt_pk_bf16_f32 v23, v24, v25
	v_cvt_pk_bf16_f32 v24, v18, v19
	v_cvt_pk_bf16_f32 v25, v20, v21
	global_store_dwordx4 v[50:51], v[22:25], off offset:256 sc1
	s_cbranch_vccnz .LBB0_409
	v_lshlrev_b64 v[18:19], 5, v[34:35]
	s_waitcnt lgkmcnt(4)
	v_lshl_add_u64 v[26:27], s[46:47], 0, v[18:19]
	v_lshl_add_u64 v[30:31], v[26:27], 0, s[96:97]
	global_load_dwordx4 v[22:25], v[26:27], off
	global_load_dwordx4 v[18:21], v[26:27], off offset:16
	v_add_co_u32_e32 v26, vcc, 0x80000, v26
	s_nop 1
	v_addc_co_u32_e32 v27, vcc, 0, v27, vcc
	s_waitcnt lgkmcnt(0)
	global_load_dwordx4 v[26:29], v[26:27], off
	s_nop 0
	global_load_dwordx4 v[30:33], v[30:31], off offset:16
	s_and_b64 vcc, exec, s[42:43]
	s_cbranch_vccz .LBB0_410
	s_branch .LBB0_413

; __device__ __forceinline__ unsigned cvt_pk_bf16(float lo, float hi) { unsigned r; asm volatile("v_cvt_pk_bf16_f32 %0, %1, %2" : "=v"(r) : "v"(lo), "v"(hi)); return r; }
;     __device__ __forceinline__ void operator()(const f32x4 (&acc)[2][2][4][2], const Unit& u, int wr, int wc, int fr, int fq) const {
;     ...
;                 for (int m = 0; m < 4; ++m) { const int row = row0 + ai * HALF + m * 16; bf16_t* rowp = O + (size_t)row * ldc + col0;
;                     f32x4 c0 = {1.f, 1.f, 1.f, 1.f}, c1 = c0, s0 = {0.f, 0.f, 0.f, 0.f}, s1 = s0;
;                     if (rot) { const float* cp = G + (size_t)row * 8; c0 = *(const f32x4*)cp; c1 = *(const f32x4*)(cp + 4); s0 = *(const f32x4*)(cp + 131072); s1 = *(const f32x4*)(cp + 131072 + 4); }
; #pragma unroll
;                     for (int bj = 0; bj < 2; ++bj) { f32x4 v0 = acc[ai][bj][m][0], v1 = acc[ai][bj][m][1];
;                         if (rot) { f32x4 q0, q1;
; #pragma unroll
;                             for (int e = 0; e < 4; ++e) { q0[e] = __shfl_xor(v0[e], 16); q1[e] = __shfl_xor(v1[e], 16); }
;                             if (fq < 2) { v0 = v0 * c0 + sg * q0 * s0; v1 = v1 * c1 + sg * q1 * s1; } }
;                         u32x4 w; w.x = cvt_pk_bf16(v0[0], v0[1]); w.y = cvt_pk_bf16(v0[2], v0[3]); w.z = cvt_pk_bf16(v1[0], v1[1]); w.w = cvt_pk_bf16(v1[2], v1[3]);
;                         *(u32x4*)(rowp + bj * HALF) = w; } }
.LBB0_413:
	s_waitcnt lgkmcnt(6)
	v_mul_lo_u32 v36, s45, v34
	s_waitcnt lgkmcnt(4)
	v_mul_lo_u32 v37, s44, v35
	v_mad_u64_u32 v[34:35], s[12:13], s44, v34, 0
	v_add3_u32 v35, v35, v37, v36
	v_lshl_add_u64 v[34:35], v[34:35], 1, s[8:9]
	v_lshl_add_u64 v[34:35], v[172:173], 1, v[34:35]
	s_and_b64 vcc, exec, s[42:43]
	v_cvt_pk_bf16_f32 v14, v14, v15
	v_cvt_pk_bf16_f32 v15, v16, v17
	v_cvt_pk_bf16_f32 v16, v10, v11
	v_cvt_pk_bf16_f32 v17, v12, v13
	global_store_dwordx4 v[34:35], v[14:17], off sc1
	s_cbranch_vccnz .LBB0_417
	v_and_b32_e32 v11, 64, v198
	v_xor_b32_e32 v10, 16, v198
	v_add_u32_e32 v11, 64, v11
	v_cmp_lt_i32_e32 vcc, v10, v11
	s_nop 1
	v_cndmask_b32_e32 v10, v198, v10, vcc
	v_lshlrev_b32_e32 v13, 2, v10
	ds_bpermute_b32 v14, v13, v6
	ds_bpermute_b32 v10, v13, v2
	ds_bpermute_b32 v15, v13, v7
	ds_bpermute_b32 v11, v13, v3
	ds_bpermute_b32 v16, v13, v8
	ds_bpermute_b32 v12, v13, v4
	ds_bpermute_b32 v17, v13, v9
	ds_bpermute_b32 v13, v13, v5
	s_and_saveexec_b64 s[12:13], s[38:39]
	s_cbranch_execz .LBB0_416
	s_waitcnt lgkmcnt(1)
	v_pk_mul_f32 v[16:17], v[150:151], v[16:17]
	v_pk_mul_f32 v[14:15], v[148:149], v[14:15]
	s_waitcnt lgkmcnt(0)
	v_pk_mul_f32 v[12:13], v[150:151], v[12:13]
	v_pk_mul_f32 v[10:11], v[148:149], v[10:11]
	s_waitcnt vmcnt(2)
	v_pk_mul_f32 v[16:17], v[28:29], v[16:17]
	v_pk_mul_f32 v[14:15], v[26:27], v[14:15]
	s_waitcnt vmcnt(1)
	v_pk_mul_f32 v[12:13], v[32:33], v[12:13]
	v_pk_mul_f32 v[10:11], v[30:31], v[10:11]
	v_pk_fma_f32 v[8:9], v[8:9], v[24:25], v[16:17]
	v_pk_fma_f32 v[6:7], v[6:7], v[22:23], v[14:15]
	v_pk_fma_f32 v[4:5], v[4:5], v[20:21], v[12:13]
	v_pk_fma_f32 v[2:3], v[2:3], v[18:19], v[10:11]

; __device__ __forceinline__ unsigned cvt_pk_bf16(float lo, float hi) { unsigned r; asm volatile("v_cvt_pk_bf16_f32 %0, %1, %2" : "=v"(r) : "v"(lo), "v"(hi)); return r; }
;     __device__ __forceinline__ void operator()(const f32x4 (&acc)[2][2][4][2], const Unit& u, int wr, int wc, int fr, int fq) const {
;     ...
;                         u32x4 w; w.x = cvt_pk_bf16(v0[0], v0[1]); w.y = cvt_pk_bf16(v0[2], v0[3]); w.z = cvt_pk_bf16(v1[0], v1[1]); w.w = cvt_pk_bf16(v1[2], v1[3]);
;                         *(u32x4*)(rowp + bj * HALF) = w; } }
.LBB0_417:
	v_cvt_pk_bf16_f32 v6, v6, v7
	v_cvt_pk_bf16_f32 v7, v8, v9
	v_cvt_pk_bf16_f32 v8, v2, v3
	v_cvt_pk_bf16_f32 v9, v4, v5
	global_store_dwordx4 v[34:35], v[6:9], off offset:256 sc1
